# packed f32 ops split into scalar pairs also in the GEMM epilogues and the attention item epilogue
# speedup vs baseline: 1.0138x; 1.0002x over previous
.LBB0_74:
	s_cmp_lt_i32 s72, 4
	s_cselect_b64 vcc, -1, 0
	v_cndmask_b32_e32 v148, 1.0, v160, vcc
	s_and_b32 s9, s72, -4
	v_mul_f32_e32 v124, v148, v124
	v_mul_f32_e32 v125, v148, v125
	v_mul_f32_e32 v126, v148, v126
	v_mul_f32_e32 v127, v148, v127
	v_mul_f32_e32 v120, v148, v120
	v_mul_f32_e32 v121, v148, v121
	s_cmp_eq_u32 s9, 4
	v_cvt_pk_bf16_f32 v124, v124, v125
	v_cvt_pk_bf16_f32 v125, v126, v127
	v_cvt_pk_bf16_f32 v126, v120, v121
	v_mul_f32_e32 v120, v148, v122
	v_mul_f32_e32 v121, v148, v123
	s_cselect_b64 s[10:11], -1, 0
	s_cmp_lg_u32 s9, 4
	v_cvt_pk_bf16_f32 v127, v120, v121
	s_cbranch_scc1 .LBB0_78
	v_and_b32_e32 v121, 0xffff0000, v124
	v_lshlrev_b32_e32 v120, 16, v124
	v_mul_f32_e32 v121, v121, v121
	v_and_b32_e32 v122, 0xffff0000, v125
	v_fmac_f32_e32 v121, v120, v120
	v_lshlrev_b32_e32 v120, 16, v125
	v_mul_f32_e32 v122, v122, v122
	v_fmac_f32_e32 v122, v120, v120
	v_add_f32_e32 v120, v121, v122
	v_and_b32_e32 v122, 0xffff0000, v126
	v_lshlrev_b32_e32 v121, 16, v126
	v_mul_f32_e32 v122, v122, v122
	v_fmac_f32_e32 v122, v121, v121
	v_add_f32_e32 v120, v120, v122
	v_and_b32_e32 v122, 0xffff0000, v127
	v_lshlrev_b32_e32 v121, 16, v127
	v_mul_f32_e32 v122, v122, v122
	v_fmac_f32_e32 v122, v121, v121
	v_add_f32_e32 v120, v122, v120
	v_and_b32_e32 v122, 64, v161
	v_xor_b32_e32 v121, 16, v161
	v_add_u32_e32 v122, 64, v122
	v_cmp_lt_i32_e32 vcc, v121, v122
	s_nop 1
	v_cndmask_b32_e32 v121, v161, v121, vcc
	v_lshlrev_b32_e32 v121, 2, v121
	ds_bpermute_b32 v121, v121, v120
	s_waitcnt lgkmcnt(0)
	v_add_f32_e32 v120, v120, v121
	v_xor_b32_e32 v121, 32, v161
	v_cmp_lt_i32_e32 vcc, v121, v122
	s_nop 1
	v_cndmask_b32_e32 v121, v161, v121, vcc
	v_lshlrev_b32_e32 v121, 2, v121
	ds_bpermute_b32 v121, v121, v120
	s_and_saveexec_b64 s[78:79], s[0:1]
	s_cbranch_execz .LBB0_77
	s_waitcnt lgkmcnt(0)
	v_add_f32_e32 v120, v120, v121
	v_add_u32_e32 v121, s99, v156
	ds_write_b32 v121, v120

.LBB0_82:
	v_mov_b32_e32 v149, v148
	v_mul_f32_e32 v116, v148, v116
	v_mul_f32_e32 v117, v149, v117
	v_mul_f32_e32 v118, v148, v118
	v_mul_f32_e32 v119, v149, v119
	v_mul_f32_e32 v112, v148, v112
	v_mul_f32_e32 v113, v149, v113
	v_cvt_pk_bf16_f32 v116, v116, v117
	v_cvt_pk_bf16_f32 v117, v118, v119
	v_cvt_pk_bf16_f32 v118, v112, v113
	v_mul_f32_e32 v112, v148, v114
	v_mul_f32_e32 v113, v149, v115
	v_cndmask_b32_e64 v114, 0, 1, s[10:11]
	v_cmp_ne_u32_e64 s[8:9], 1, v114
	s_andn2_b64 vcc, exec, s[10:11]
	v_cvt_pk_bf16_f32 v119, v112, v113
	s_cbranch_vccnz .LBB0_86
	v_and_b32_e32 v113, 0xffff0000, v116
	v_lshlrev_b32_e32 v112, 16, v116
	v_mul_f32_e32 v113, v113, v113
	v_and_b32_e32 v114, 0xffff0000, v117
	v_fmac_f32_e32 v113, v112, v112
	v_lshlrev_b32_e32 v112, 16, v117
	v_mul_f32_e32 v114, v114, v114
	v_fmac_f32_e32 v114, v112, v112
	v_add_f32_e32 v112, v113, v114
	v_and_b32_e32 v114, 0xffff0000, v118
	v_lshlrev_b32_e32 v113, 16, v118
	v_mul_f32_e32 v114, v114, v114
	v_fmac_f32_e32 v114, v113, v113
	v_add_f32_e32 v112, v112, v114
	v_and_b32_e32 v114, 0xffff0000, v119
	v_lshlrev_b32_e32 v113, 16, v119
	v_mul_f32_e32 v114, v114, v114
	v_fmac_f32_e32 v114, v113, v113
	v_add_f32_e32 v112, v114, v112
	v_and_b32_e32 v114, 64, v161
	v_xor_b32_e32 v113, 16, v161
	v_add_u32_e32 v114, 64, v114
	v_cmp_lt_i32_e32 vcc, v113, v114
	s_nop 1
	v_cndmask_b32_e32 v113, v161, v113, vcc
	v_lshlrev_b32_e32 v113, 2, v113
	ds_bpermute_b32 v113, v113, v112
	s_waitcnt lgkmcnt(0)
	v_add_f32_e32 v112, v112, v113
	v_xor_b32_e32 v113, 32, v161
	v_cmp_lt_i32_e32 vcc, v113, v114
	s_nop 1
	v_cndmask_b32_e32 v113, v161, v113, vcc
	v_lshlrev_b32_e32 v113, 2, v113
	ds_bpermute_b32 v113, v113, v112
	s_and_saveexec_b64 s[10:11], s[0:1]
	s_cbranch_execz .LBB0_85
	s_waitcnt lgkmcnt(0)
	v_add_f32_e32 v112, v112, v113
	v_add_u32_e32 v113, s99, v156
	ds_write_b32 v113, v112 offset:4

.LBB0_90:
	v_mul_f32_e32 v108, v148, v108
	v_mul_f32_e32 v109, v149, v109
	v_mul_f32_e32 v110, v148, v110
	v_mul_f32_e32 v111, v149, v111
	v_mul_f32_e32 v104, v148, v104
	v_mul_f32_e32 v105, v149, v105
	v_cvt_pk_bf16_f32 v108, v108, v109
	v_cvt_pk_bf16_f32 v109, v110, v111
	v_cvt_pk_bf16_f32 v110, v104, v105
	v_mul_f32_e32 v104, v148, v106
	v_mul_f32_e32 v105, v149, v107
	s_and_b64 vcc, exec, s[8:9]
	v_cvt_pk_bf16_f32 v111, v104, v105
	s_cbranch_vccnz .LBB0_94
	v_and_b32_e32 v105, 0xffff0000, v108
	v_lshlrev_b32_e32 v104, 16, v108
	v_mul_f32_e32 v105, v105, v105
	v_and_b32_e32 v106, 0xffff0000, v109
	v_fmac_f32_e32 v105, v104, v104
	v_lshlrev_b32_e32 v104, 16, v109
	v_mul_f32_e32 v106, v106, v106
	v_fmac_f32_e32 v106, v104, v104
	v_add_f32_e32 v104, v105, v106
	v_and_b32_e32 v106, 0xffff0000, v110
	v_lshlrev_b32_e32 v105, 16, v110
	v_mul_f32_e32 v106, v106, v106
	v_fmac_f32_e32 v106, v105, v105
	v_add_f32_e32 v104, v104, v106
	v_and_b32_e32 v106, 0xffff0000, v111
	v_lshlrev_b32_e32 v105, 16, v111
	v_mul_f32_e32 v106, v106, v106
	v_fmac_f32_e32 v106, v105, v105
	v_add_f32_e32 v104, v106, v104
	v_and_b32_e32 v106, 64, v161
	v_xor_b32_e32 v105, 16, v161
	v_add_u32_e32 v106, 64, v106
	v_cmp_lt_i32_e32 vcc, v105, v106
	s_nop 1
	v_cndmask_b32_e32 v105, v161, v105, vcc
	v_lshlrev_b32_e32 v105, 2, v105
	ds_bpermute_b32 v105, v105, v104
	s_waitcnt lgkmcnt(0)
	v_add_f32_e32 v104, v104, v105
	v_xor_b32_e32 v105, 32, v161
	v_cmp_lt_i32_e32 vcc, v105, v106
	s_nop 1
	v_cndmask_b32_e32 v105, v161, v105, vcc
	v_lshlrev_b32_e32 v105, 2, v105
	ds_bpermute_b32 v105, v105, v104
	s_and_saveexec_b64 s[80:81], s[0:1]
	s_cbranch_execz .LBB0_93
	s_waitcnt lgkmcnt(0)
	v_add_f32_e32 v104, v104, v105
	v_add_u32_e32 v105, s99, v156
	ds_write_b32 v105, v104 offset:128

.LBB0_98:
	v_mul_f32_e32 v100, v148, v100
	v_mul_f32_e32 v101, v149, v101
	v_mul_f32_e32 v102, v148, v102
	v_mul_f32_e32 v103, v149, v103
	v_mul_f32_e32 v96, v148, v96
	v_mul_f32_e32 v97, v149, v97
	v_cvt_pk_bf16_f32 v100, v100, v101
	v_cvt_pk_bf16_f32 v101, v102, v103
	v_cvt_pk_bf16_f32 v102, v96, v97
	v_mul_f32_e32 v96, v148, v98
	v_mul_f32_e32 v97, v149, v99
	s_and_b64 vcc, exec, s[8:9]
	v_cvt_pk_bf16_f32 v103, v96, v97
	s_cbranch_vccz .LBB0_175
	s_and_b64 vcc, exec, s[10:11]
	s_mov_b64 s[80:81], -1
	s_cbranch_vccz .LBB0_178

.LBB0_102:
	v_mul_f32_e32 v92, v148, v92
	v_mul_f32_e32 v93, v149, v93
	v_mul_f32_e32 v94, v148, v94
	v_mul_f32_e32 v95, v149, v95
	v_mul_f32_e32 v88, v148, v88
	v_mul_f32_e32 v89, v149, v89
	v_cvt_pk_bf16_f32 v92, v92, v93
	v_cvt_pk_bf16_f32 v93, v94, v95
	v_cvt_pk_bf16_f32 v94, v88, v89
	v_mul_f32_e32 v88, v148, v90
	v_mul_f32_e32 v89, v149, v91
	s_and_b64 vcc, exec, s[8:9]
	v_cvt_pk_bf16_f32 v95, v88, v89
	s_cbranch_vccnz .LBB0_106
	v_and_b32_e32 v89, 0xffff0000, v92
	v_lshlrev_b32_e32 v88, 16, v92
	v_mul_f32_e32 v89, v89, v89
	v_and_b32_e32 v90, 0xffff0000, v93
	v_fmac_f32_e32 v89, v88, v88
	v_lshlrev_b32_e32 v88, 16, v93
	v_mul_f32_e32 v90, v90, v90
	v_fmac_f32_e32 v90, v88, v88
	v_add_f32_e32 v88, v89, v90
	v_and_b32_e32 v90, 0xffff0000, v94
	v_lshlrev_b32_e32 v89, 16, v94
	v_mul_f32_e32 v90, v90, v90
	v_fmac_f32_e32 v90, v89, v89
	v_add_f32_e32 v88, v88, v90
	v_and_b32_e32 v90, 0xffff0000, v95
	v_lshlrev_b32_e32 v89, 16, v95
	v_mul_f32_e32 v90, v90, v90
	v_fmac_f32_e32 v90, v89, v89
	v_add_f32_e32 v88, v90, v88
	v_and_b32_e32 v90, 64, v161
	v_xor_b32_e32 v89, 16, v161
	v_add_u32_e32 v90, 64, v90
	v_cmp_lt_i32_e32 vcc, v89, v90
	s_nop 1
	v_cndmask_b32_e32 v89, v161, v89, vcc
	v_lshlrev_b32_e32 v89, 2, v89
	ds_bpermute_b32 v89, v89, v88
	s_waitcnt lgkmcnt(0)
	v_add_f32_e32 v88, v88, v89
	v_xor_b32_e32 v89, 32, v161
	v_cmp_lt_i32_e32 vcc, v89, v90
	s_nop 1
	v_cndmask_b32_e32 v89, v161, v89, vcc
	v_lshlrev_b32_e32 v89, 2, v89
	ds_bpermute_b32 v89, v89, v88
	s_and_saveexec_b64 s[80:81], s[0:1]
	s_cbranch_execz .LBB0_105
	s_waitcnt lgkmcnt(0)
	v_add_f32_e32 v88, v88, v89
	v_add_u32_e32 v89, s99, v156
	ds_write_b32 v89, v88 offset:256

.LBB0_110:
	v_mul_f32_e32 v84, v148, v84
	v_mul_f32_e32 v85, v149, v85
	v_mul_f32_e32 v86, v148, v86
	v_mul_f32_e32 v87, v149, v87
	v_mul_f32_e32 v80, v148, v80
	v_mul_f32_e32 v81, v149, v81
	v_cvt_pk_bf16_f32 v84, v84, v85
	v_cvt_pk_bf16_f32 v85, v86, v87
	v_cvt_pk_bf16_f32 v86, v80, v81
	v_mul_f32_e32 v80, v148, v82
	v_mul_f32_e32 v81, v149, v83
	s_and_b64 vcc, exec, s[8:9]
	v_cvt_pk_bf16_f32 v87, v80, v81
	s_cbranch_vccz .LBB0_179
	s_and_b64 vcc, exec, s[10:11]
	s_mov_b64 s[80:81], -1
	s_cbranch_vccz .LBB0_182

.LBB0_114:
	v_mul_f32_e32 v76, v148, v76
	v_mul_f32_e32 v77, v149, v77
	v_mul_f32_e32 v78, v148, v78
	v_mul_f32_e32 v79, v149, v79
	v_mul_f32_e32 v72, v148, v72
	v_mul_f32_e32 v73, v149, v73
	v_cvt_pk_bf16_f32 v76, v76, v77
	v_cvt_pk_bf16_f32 v77, v78, v79
	v_cvt_pk_bf16_f32 v78, v72, v73
	v_mul_f32_e32 v72, v148, v74
	v_mul_f32_e32 v73, v149, v75
	s_and_b64 vcc, exec, s[8:9]
	v_cvt_pk_bf16_f32 v79, v72, v73
	s_cbranch_vccnz .LBB0_118
	v_and_b32_e32 v73, 0xffff0000, v76
	v_lshlrev_b32_e32 v72, 16, v76
	v_mul_f32_e32 v73, v73, v73
	v_and_b32_e32 v74, 0xffff0000, v77
	v_fmac_f32_e32 v73, v72, v72
	v_lshlrev_b32_e32 v72, 16, v77
	v_mul_f32_e32 v74, v74, v74
	v_fmac_f32_e32 v74, v72, v72
	v_add_f32_e32 v72, v73, v74
	v_and_b32_e32 v74, 0xffff0000, v78
	v_lshlrev_b32_e32 v73, 16, v78
	v_mul_f32_e32 v74, v74, v74
	v_fmac_f32_e32 v74, v73, v73
	v_add_f32_e32 v72, v72, v74
	v_and_b32_e32 v74, 0xffff0000, v79
	v_lshlrev_b32_e32 v73, 16, v79
	v_mul_f32_e32 v74, v74, v74
	v_fmac_f32_e32 v74, v73, v73
	v_add_f32_e32 v72, v74, v72
	v_and_b32_e32 v74, 64, v161
	v_xor_b32_e32 v73, 16, v161
	v_add_u32_e32 v74, 64, v74
	v_cmp_lt_i32_e32 vcc, v73, v74
	s_nop 1
	v_cndmask_b32_e32 v73, v161, v73, vcc
	v_lshlrev_b32_e32 v73, 2, v73
	ds_bpermute_b32 v73, v73, v72
	s_waitcnt lgkmcnt(0)
	v_add_f32_e32 v72, v72, v73
	v_xor_b32_e32 v73, 32, v161
	v_cmp_lt_i32_e32 vcc, v73, v74
	s_nop 1
	v_cndmask_b32_e32 v73, v161, v73, vcc
	v_lshlrev_b32_e32 v73, 2, v73
	ds_bpermute_b32 v73, v73, v72
	s_and_saveexec_b64 s[80:81], s[0:1]
	s_cbranch_execz .LBB0_117
	s_waitcnt lgkmcnt(0)
	v_add_f32_e32 v72, v72, v73
	v_add_u32_e32 v73, s99, v156
	ds_write_b32 v73, v72 offset:384

.LBB0_122:
	v_mul_f32_e32 v68, v148, v68
	v_mul_f32_e32 v69, v149, v69
	v_mul_f32_e32 v70, v148, v70
	v_mul_f32_e32 v71, v149, v71
	v_mul_f32_e32 v64, v148, v64
	v_mul_f32_e32 v65, v149, v65
	v_cvt_pk_bf16_f32 v68, v68, v69
	v_cvt_pk_bf16_f32 v69, v70, v71
	v_cvt_pk_bf16_f32 v70, v64, v65
	v_mul_f32_e32 v64, v148, v66
	v_mul_f32_e32 v65, v149, v67
	s_and_b64 vcc, exec, s[8:9]
	v_cvt_pk_bf16_f32 v71, v64, v65
	s_cbranch_vccz .LBB0_183
	s_and_b64 vcc, exec, s[10:11]
	s_mov_b64 s[78:79], -1
	s_cbranch_vccz .LBB0_186

.LBB0_126:
	v_mul_f32_e32 v60, v148, v60
	v_mul_f32_e32 v61, v149, v61
	v_mul_f32_e32 v62, v148, v62
	v_mul_f32_e32 v63, v149, v63
	v_mul_f32_e32 v56, v148, v56
	v_mul_f32_e32 v57, v149, v57
	v_cvt_pk_bf16_f32 v60, v60, v61
	v_cvt_pk_bf16_f32 v61, v62, v63
	v_cvt_pk_bf16_f32 v62, v56, v57
	v_mul_f32_e32 v56, v148, v58
	v_mul_f32_e32 v57, v149, v59
	s_and_b64 vcc, exec, s[8:9]
	v_cvt_pk_bf16_f32 v63, v56, v57
	s_cbranch_vccnz .LBB0_130
	v_and_b32_e32 v57, 0xffff0000, v60
	v_lshlrev_b32_e32 v56, 16, v60
	v_mul_f32_e32 v57, v57, v57
	v_and_b32_e32 v58, 0xffff0000, v61
	v_fmac_f32_e32 v57, v56, v56
	v_lshlrev_b32_e32 v56, 16, v61
	v_mul_f32_e32 v58, v58, v58
	v_fmac_f32_e32 v58, v56, v56
	v_add_f32_e32 v56, v57, v58
	v_and_b32_e32 v58, 0xffff0000, v62
	v_lshlrev_b32_e32 v57, 16, v62
	v_mul_f32_e32 v58, v58, v58
	v_fmac_f32_e32 v58, v57, v57
	v_add_f32_e32 v56, v56, v58
	v_and_b32_e32 v58, 0xffff0000, v63
	v_lshlrev_b32_e32 v57, 16, v63
	v_mul_f32_e32 v58, v58, v58
	v_fmac_f32_e32 v58, v57, v57
	v_add_f32_e32 v56, v58, v56
	v_and_b32_e32 v58, 64, v161
	v_xor_b32_e32 v57, 16, v161
	v_add_u32_e32 v58, 64, v58
	v_cmp_lt_i32_e32 vcc, v57, v58
	s_nop 1
	v_cndmask_b32_e32 v57, v161, v57, vcc
	v_lshlrev_b32_e32 v57, 2, v57
	ds_bpermute_b32 v57, v57, v56
	s_waitcnt lgkmcnt(0)
	v_add_f32_e32 v56, v56, v57
	v_xor_b32_e32 v57, 32, v161
	v_cmp_lt_i32_e32 vcc, v57, v58
	s_nop 1
	v_cndmask_b32_e32 v57, v161, v57, vcc
	v_lshlrev_b32_e32 v57, 2, v57
	ds_bpermute_b32 v57, v57, v56
	s_and_saveexec_b64 s[78:79], s[0:1]
	s_cbranch_execz .LBB0_129
	s_waitcnt lgkmcnt(0)
	v_add_f32_e32 v56, v56, v57
	v_add_u32_e32 v57, s99, v156
	ds_write_b32 v57, v56 offset:512

.LBB0_134:
	v_mul_f32_e32 v52, v148, v52
	v_mul_f32_e32 v53, v149, v53
	v_mul_f32_e32 v54, v148, v54
	v_mul_f32_e32 v55, v149, v55
	v_mul_f32_e32 v48, v148, v48
	v_mul_f32_e32 v49, v149, v49
	v_cvt_pk_bf16_f32 v52, v52, v53
	v_cvt_pk_bf16_f32 v53, v54, v55
	v_cvt_pk_bf16_f32 v54, v48, v49
	v_mul_f32_e32 v48, v148, v50
	v_mul_f32_e32 v49, v149, v51
	s_and_b64 vcc, exec, s[8:9]
	v_cvt_pk_bf16_f32 v55, v48, v49
	s_cbranch_vccz .LBB0_187
	s_and_b64 vcc, exec, s[10:11]
	s_mov_b64 s[80:81], -1
	s_cbranch_vccz .LBB0_190

.LBB0_138:
	v_mul_f32_e32 v44, v148, v44
	v_mul_f32_e32 v45, v149, v45
	v_mul_f32_e32 v46, v148, v46
	v_mul_f32_e32 v47, v149, v47
	v_mul_f32_e32 v40, v148, v40
	v_mul_f32_e32 v41, v149, v41
	v_cvt_pk_bf16_f32 v44, v44, v45
	v_cvt_pk_bf16_f32 v45, v46, v47
	v_cvt_pk_bf16_f32 v46, v40, v41
	v_mul_f32_e32 v40, v148, v42
	v_mul_f32_e32 v41, v149, v43
	s_and_b64 vcc, exec, s[8:9]
	v_cvt_pk_bf16_f32 v47, v40, v41
	s_cbranch_vccnz .LBB0_142
	v_and_b32_e32 v41, 0xffff0000, v44
	v_lshlrev_b32_e32 v40, 16, v44
	v_mul_f32_e32 v41, v41, v41
	v_and_b32_e32 v42, 0xffff0000, v45
	v_fmac_f32_e32 v41, v40, v40
	v_lshlrev_b32_e32 v40, 16, v45
	v_mul_f32_e32 v42, v42, v42
	v_fmac_f32_e32 v42, v40, v40
	v_add_f32_e32 v40, v41, v42
	v_and_b32_e32 v42, 0xffff0000, v46
	v_lshlrev_b32_e32 v41, 16, v46
	v_mul_f32_e32 v42, v42, v42
	v_fmac_f32_e32 v42, v41, v41
	v_add_f32_e32 v40, v40, v42
	v_and_b32_e32 v42, 0xffff0000, v47
	v_lshlrev_b32_e32 v41, 16, v47
	v_mul_f32_e32 v42, v42, v42
	v_fmac_f32_e32 v42, v41, v41
	v_add_f32_e32 v40, v42, v40
	v_and_b32_e32 v42, 64, v161
	v_xor_b32_e32 v41, 16, v161
	v_add_u32_e32 v42, 64, v42
	v_cmp_lt_i32_e32 vcc, v41, v42
	s_nop 1
	v_cndmask_b32_e32 v41, v161, v41, vcc
	v_lshlrev_b32_e32 v41, 2, v41
	ds_bpermute_b32 v41, v41, v40
	s_waitcnt lgkmcnt(0)
	v_add_f32_e32 v40, v40, v41
	v_xor_b32_e32 v41, 32, v161
	v_cmp_lt_i32_e32 vcc, v41, v42
	s_nop 1
	v_cndmask_b32_e32 v41, v161, v41, vcc
	v_lshlrev_b32_e32 v41, 2, v41
	ds_bpermute_b32 v41, v41, v40
	s_and_saveexec_b64 s[80:81], s[0:1]
	s_cbranch_execz .LBB0_141
	s_waitcnt lgkmcnt(0)
	v_add_f32_e32 v40, v40, v41
	v_add_u32_e32 v41, s99, v156
	ds_write_b32 v41, v40 offset:640

.LBB0_146:
	v_mul_f32_e32 v36, v148, v36
	v_mul_f32_e32 v37, v149, v37
	v_mul_f32_e32 v38, v148, v38
	v_mul_f32_e32 v39, v149, v39
	v_mul_f32_e32 v32, v148, v32
	v_mul_f32_e32 v33, v149, v33
	v_cvt_pk_bf16_f32 v36, v36, v37
	v_cvt_pk_bf16_f32 v37, v38, v39
	v_cvt_pk_bf16_f32 v38, v32, v33
	v_mul_f32_e32 v32, v148, v34
	v_mul_f32_e32 v33, v149, v35
	s_and_b64 vcc, exec, s[8:9]
	v_cvt_pk_bf16_f32 v39, v32, v33
	s_cbranch_vccz .LBB0_191
	s_and_b64 vcc, exec, s[10:11]
	s_mov_b64 s[80:81], -1
	s_cbranch_vccz .LBB0_194

.LBB0_150:
	v_mul_f32_e32 v28, v148, v28
	v_mul_f32_e32 v29, v149, v29
	v_mul_f32_e32 v30, v148, v30
	v_mul_f32_e32 v31, v149, v31
	v_mul_f32_e32 v24, v148, v24
	v_mul_f32_e32 v25, v149, v25
	v_cvt_pk_bf16_f32 v28, v28, v29
	v_cvt_pk_bf16_f32 v29, v30, v31
	v_cvt_pk_bf16_f32 v30, v24, v25
	v_mul_f32_e32 v24, v148, v26
	v_mul_f32_e32 v25, v149, v27
	s_and_b64 vcc, exec, s[8:9]
	v_cvt_pk_bf16_f32 v31, v24, v25
	s_cbranch_vccnz .LBB0_154
	v_and_b32_e32 v25, 0xffff0000, v28
	v_lshlrev_b32_e32 v24, 16, v28
	v_mul_f32_e32 v25, v25, v25
	v_and_b32_e32 v26, 0xffff0000, v29
	v_fmac_f32_e32 v25, v24, v24
	v_lshlrev_b32_e32 v24, 16, v29
	v_mul_f32_e32 v26, v26, v26
	v_fmac_f32_e32 v26, v24, v24
	v_add_f32_e32 v24, v25, v26
	v_and_b32_e32 v26, 0xffff0000, v30
	v_lshlrev_b32_e32 v25, 16, v30
	v_mul_f32_e32 v26, v26, v26
	v_fmac_f32_e32 v26, v25, v25
	v_add_f32_e32 v24, v24, v26
	v_and_b32_e32 v26, 0xffff0000, v31
	v_lshlrev_b32_e32 v25, 16, v31
	v_mul_f32_e32 v26, v26, v26
	v_fmac_f32_e32 v26, v25, v25
	v_add_f32_e32 v24, v26, v24
	v_and_b32_e32 v26, 64, v161
	v_xor_b32_e32 v25, 16, v161
	v_add_u32_e32 v26, 64, v26
	v_cmp_lt_i32_e32 vcc, v25, v26
	s_nop 1
	v_cndmask_b32_e32 v25, v161, v25, vcc
	v_lshlrev_b32_e32 v25, 2, v25
	ds_bpermute_b32 v25, v25, v24
	s_waitcnt lgkmcnt(0)
	v_add_f32_e32 v24, v24, v25
	v_xor_b32_e32 v25, 32, v161
	v_cmp_lt_i32_e32 vcc, v25, v26
	s_nop 1
	v_cndmask_b32_e32 v25, v161, v25, vcc
	v_lshlrev_b32_e32 v25, 2, v25
	ds_bpermute_b32 v25, v25, v24
	s_and_saveexec_b64 s[80:81], s[0:1]
	s_cbranch_execz .LBB0_153
	s_waitcnt lgkmcnt(0)
	v_add_f32_e32 v24, v24, v25
	v_add_u32_e32 v25, s99, v156
	ds_write_b32 v25, v24 offset:768

.LBB0_158:
	v_mul_f32_e32 v20, v148, v20
	v_mul_f32_e32 v21, v149, v21
	v_mul_f32_e32 v22, v148, v22
	v_mul_f32_e32 v23, v149, v23
	v_mul_f32_e32 v16, v148, v16
	v_mul_f32_e32 v17, v149, v17
	v_cvt_pk_bf16_f32 v20, v20, v21
	v_cvt_pk_bf16_f32 v21, v22, v23
	v_cvt_pk_bf16_f32 v22, v16, v17
	v_mul_f32_e32 v16, v148, v18
	v_mul_f32_e32 v17, v149, v19
	s_and_b64 vcc, exec, s[8:9]
	v_cvt_pk_bf16_f32 v23, v16, v17
	s_cbranch_vccz .LBB0_195
	s_and_b64 vcc, exec, s[10:11]
	s_mov_b64 s[80:81], -1
	s_cbranch_vccz .LBB0_198

.LBB0_162:
	v_mul_f32_e32 v12, v148, v12
	v_mul_f32_e32 v13, v149, v13
	v_mul_f32_e32 v14, v148, v14
	v_mul_f32_e32 v15, v149, v15
	v_mul_f32_e32 v8, v148, v8
	v_mul_f32_e32 v9, v149, v9
	v_cvt_pk_bf16_f32 v12, v12, v13
	v_cvt_pk_bf16_f32 v13, v14, v15
	v_cvt_pk_bf16_f32 v14, v8, v9
	v_mul_f32_e32 v8, v148, v10
	v_mul_f32_e32 v9, v149, v11
	s_and_b64 vcc, exec, s[8:9]
	v_cvt_pk_bf16_f32 v15, v8, v9
	s_cbranch_vccnz .LBB0_166
	v_and_b32_e32 v9, 0xffff0000, v12
	v_lshlrev_b32_e32 v8, 16, v12
	v_mul_f32_e32 v9, v9, v9
	v_and_b32_e32 v10, 0xffff0000, v13
	v_fmac_f32_e32 v9, v8, v8
	v_lshlrev_b32_e32 v8, 16, v13
	v_mul_f32_e32 v10, v10, v10
	v_fmac_f32_e32 v10, v8, v8
	v_add_f32_e32 v8, v9, v10
	v_and_b32_e32 v10, 0xffff0000, v14
	v_lshlrev_b32_e32 v9, 16, v14
	v_mul_f32_e32 v10, v10, v10
	v_fmac_f32_e32 v10, v9, v9
	v_add_f32_e32 v8, v8, v10
	v_and_b32_e32 v10, 0xffff0000, v15
	v_lshlrev_b32_e32 v9, 16, v15
	v_mul_f32_e32 v10, v10, v10
	v_fmac_f32_e32 v10, v9, v9
	v_add_f32_e32 v8, v10, v8
	v_and_b32_e32 v10, 64, v161
	v_xor_b32_e32 v9, 16, v161
	v_add_u32_e32 v10, 64, v10
	v_cmp_lt_i32_e32 vcc, v9, v10
	s_nop 1
	v_cndmask_b32_e32 v9, v161, v9, vcc
	v_lshlrev_b32_e32 v9, 2, v9
	ds_bpermute_b32 v9, v9, v8
	s_waitcnt lgkmcnt(0)
	v_add_f32_e32 v8, v8, v9
	v_xor_b32_e32 v9, 32, v161
	v_cmp_lt_i32_e32 vcc, v9, v10
	s_nop 1
	v_cndmask_b32_e32 v9, v161, v9, vcc
	v_lshlrev_b32_e32 v9, 2, v9
	ds_bpermute_b32 v9, v9, v8
	s_and_saveexec_b64 s[80:81], s[0:1]
	s_cbranch_execz .LBB0_165
	s_waitcnt lgkmcnt(0)
	v_add_f32_e32 v8, v8, v9
	v_add_u32_e32 v9, s99, v156
	ds_write_b32 v9, v8 offset:896

.LBB0_170:
	v_mul_f32_e32 v4, v148, v4
	v_mul_f32_e32 v5, v149, v5
	v_mul_f32_e32 v6, v148, v6
	v_mul_f32_e32 v7, v149, v7
	v_mul_f32_e32 v0, v148, v0
	v_mul_f32_e32 v1, v149, v1
	v_cvt_pk_bf16_f32 v4, v4, v5
	v_cvt_pk_bf16_f32 v5, v6, v7
	v_cvt_pk_bf16_f32 v6, v0, v1
	v_mul_f32_e32 v0, v148, v2
	v_mul_f32_e32 v1, v149, v3
	s_and_b64 vcc, exec, s[8:9]
	v_cvt_pk_bf16_f32 v7, v0, v1
	s_cbranch_vccz .LBB0_199
	s_and_b64 vcc, exec, s[10:11]
	s_mov_b64 s[10:11], -1
	s_cbranch_vccz .LBB0_202

.LBB0_266:
	s_andn2_b64 vcc, exec, s[52:53]
	s_waitcnt lgkmcnt(0)
	s_barrier
	s_cbranch_vccnz .LBB0_229
	s_lshl_b32 s40, s5, 1
	v_lshl_add_u64 v[88:89], v[156:157], 0, s[40:41]
	v_mov_b32_e32 v155, v97
	v_lshl_add_u64 v[184:185], v[88:89], 0, v[154:155]
	s_movk_i32 s0, 0x1000
	v_add_co_u32_e32 v88, vcc, s0, v184
	s_mov_b64 s[0:1], 0x1800
	s_nop 0
	v_addc_co_u32_e32 v89, vcc, 0, v185, vcc
	global_load_dwordx2 v[130:131], v[88:89], off offset:2048
	ds_read2_b32 v[164:165], v191 offset1:32
	ds_read2_b32 v[178:179], v191 offset0:64 offset1:96
	ds_read2_b32 v[162:163], v98 offset1:32
	ds_read2_b32 v[176:177], v98 offset0:64 offset1:96
	ds_read2_b32 v[160:161], v96 offset1:32
	ds_read2_b32 v[174:175], v96 offset0:64 offset1:96
	ds_read2_b32 v[158:159], v95 offset1:32
	ds_read2_b32 v[172:173], v95 offset0:64 offset1:96
	ds_read2_b32 v[156:157], v94 offset1:32
	ds_read2_b32 v[170:171], v94 offset0:64 offset1:96
	s_waitcnt vmcnt(1)
	ds_read2_b32 v[138:139], v93 offset1:32
	ds_read2_b32 v[168:169], v93 offset0:64 offset1:96
	ds_read2_b32 v[136:137], v92 offset1:32
	ds_read2_b32 v[166:167], v92 offset0:64 offset1:96
	ds_read2_b32 v[128:129], v91 offset1:32
	ds_read2_b32 v[134:135], v91 offset0:64 offset1:96
	ds_read2_b32 v[124:125], v90 offset1:32
	ds_read2_b32 v[132:133], v90 offset0:64 offset1:96
	ds_read2_b32 v[120:121], v79 offset1:32
	ds_read2_b32 v[126:127], v79 offset0:64 offset1:96
	ds_read2_b32 v[116:117], v77 offset1:32
	ds_read2_b32 v[122:123], v77 offset0:64 offset1:96
	ds_read2_b32 v[112:113], v76 offset1:32
	ds_read2_b32 v[118:119], v76 offset0:64 offset1:96
	ds_read2_b32 v[108:109], v75 offset1:32
	ds_read2_b32 v[114:115], v75 offset0:64 offset1:96
	ds_read2_b32 v[94:95], v74 offset1:32
	ds_read2_b32 v[110:111], v74 offset0:64 offset1:96
	ds_read2_b32 v[92:93], v73 offset1:32
	ds_read2_b32 v[98:99], v73 offset0:64 offset1:96
	ds_read2_b32 v[182:183], v72 offset1:32
	ds_read2_b32 v[180:181], v72 offset0:64 offset1:96
	s_waitcnt lgkmcnt(14)
	v_fma_f32 v160, v56, v78, -v160
	v_fma_f32 v161, v57, v78, -v161
	v_fma_f32 v56, v32, v78, -v156
	v_fma_f32 v57, v33, v78, -v157
	v_fma_f32 v176, v54, v78, -v176
	v_fma_f32 v177, v55, v78, -v177
	v_fma_f32 v54, v34, v78, -v170
	v_fma_f32 v55, v35, v78, -v171
	s_waitcnt lgkmcnt(1)
	v_fma_f32 v12, v12, v78, -v182
	v_fma_f32 v13, v13, v78, -v183
	s_waitcnt lgkmcnt(0)
	v_fma_f32 v14, v14, v78, -v180
	v_fma_f32 v15, v15, v78, -v181
	v_fma_f32 v178, v50, v78, -v178
	v_fma_f32 v179, v51, v78, -v179
	v_fma_f32 v164, v48, v78, -v164
	v_fma_f32 v165, v49, v78, -v165
	v_fma_f32 v162, v52, v78, -v162
	v_fma_f32 v163, v53, v78, -v163
	v_fma_f32 v58, v58, v78, -v174
	v_fma_f32 v59, v59, v78, -v175
	v_fma_f32 v62, v62, v78, -v172
	v_fma_f32 v63, v63, v78, -v173
	v_fma_f32 v60, v60, v78, -v158
	v_fma_f32 v61, v61, v78, -v159
	v_fma_f32 v50, v38, v78, -v168
	v_fma_f32 v51, v39, v78, -v169
	v_fma_f32 v52, v36, v78, -v138
	v_fma_f32 v53, v37, v78, -v139
	v_fma_f32 v42, v42, v78, -v166
	v_fma_f32 v43, v43, v78, -v167
	v_fma_f32 v48, v40, v78, -v136
	v_fma_f32 v49, v41, v78, -v137
	v_mul_f32_e32 v158, v164, v164
	v_mul_f32_e32 v159, v165, v165
	global_load_dwordx4 v[72:75], v[144:145], off
	v_mul_f32_e32 v156, v178, v178
	v_mul_f32_e32 v157, v179, v179
	v_mul_f32_e32 v168, v162, v162
	v_mul_f32_e32 v169, v163, v163
	v_mul_f32_e32 v166, v176, v176
	v_mul_f32_e32 v167, v177, v177
	v_mul_f32_e32 v172, v160, v160
	v_mul_f32_e32 v173, v161, v161
	v_mul_f32_e32 v170, v58, v58
	v_mul_f32_e32 v171, v59, v59
	v_mul_f32_e32 v180, v60, v60
	v_mul_f32_e32 v181, v61, v61
	v_mul_f32_e32 v174, v62, v62
	v_mul_f32_e32 v175, v63, v63
	v_mul_f32_e32 v200, v56, v56
	v_mul_f32_e32 v201, v57, v57
	v_mul_f32_e32 v182, v54, v54
	v_mul_f32_e32 v183, v55, v55
	v_mul_f32_e32 v204, v52, v52
	v_mul_f32_e32 v205, v53, v53
	v_mul_f32_e32 v202, v50, v50
	v_mul_f32_e32 v203, v51, v51
	v_mul_f32_e32 v212, v48, v48
	v_mul_f32_e32 v213, v49, v49
	v_mul_f32_e32 v206, v42, v42
	v_mul_f32_e32 v207, v43, v43
	v_mul_f32_e32 v136, v12, v12
	v_mul_f32_e32 v137, v13, v13
	v_mul_f32_e32 v138, v14, v14
	v_mul_f32_e32 v139, v15, v15
	v_lshl_add_u64 v[76:77], v[184:185], 0, s[0:1]
	global_load_dwordx2 v[90:91], v[76:77], off offset:16
	global_load_dwordx2 v[184:185], v[76:77], off offset:240
	s_mov_b32 s0, 0x800000
	s_waitcnt vmcnt(3)
	v_lshlrev_b32_e32 v208, 16, v130
	v_and_b32_e32 v209, 0xffff0000, v130
	v_lshlrev_b32_e32 v130, 16, v131
	v_mul_f32_e32 v32, 0xbfb8aa3b, v208
	v_mul_f32_e32 v33, 0xbfb8aa3b, v209
	v_mul_f32_e32 v34, 0xbfb8aa3b, v130
	v_exp_f32_e32 v32, v32
	v_exp_f32_e32 v33, v33
	v_exp_f32_e32 v79, v34
	v_and_b32_e32 v131, 0xffff0000, v131
	v_mul_f32_e32 v35, 0xbfb8aa3b, v131
	v_add_f32_e32 v32, 1.0, v32
	v_add_f32_e32 v33, 1.0, v33
	v_exp_f32_e32 v96, v35
	v_rcp_f32_e32 v210, v32
	v_rcp_f32_e32 v211, v33
	v_fma_f32 v46, v46, v78, -v134
	v_fma_f32 v47, v47, v78, -v135
	v_fma_f32 v44, v44, v78, -v128
	v_fma_f32 v45, v45, v78, -v129
	v_fma_f32 v38, v18, v78, -v132
	v_fma_f32 v39, v19, v78, -v133
	v_fma_f32 v40, v16, v78, -v124
	v_fma_f32 v41, v17, v78, -v125
	v_fma_f32 v34, v22, v78, -v126
	v_fma_f32 v35, v23, v78, -v127
	v_fma_f32 v36, v20, v78, -v120
	v_fma_f32 v37, v21, v78, -v121
	v_fma_f32 v26, v26, v78, -v122
	v_fma_f32 v27, v27, v78, -v123
	v_fma_f32 v32, v24, v78, -v116
	v_fma_f32 v33, v25, v78, -v117
	v_fma_f32 v22, v30, v78, -v118
	v_fma_f32 v23, v31, v78, -v119
	v_fma_f32 v24, v28, v78, -v112
	v_fma_f32 v25, v29, v78, -v113
	v_fma_f32 v18, v2, v78, -v114
	v_fma_f32 v19, v3, v78, -v115
	v_fma_f32 v20, v0, v78, -v108
	v_fma_f32 v21, v1, v78, -v109
	v_fma_f32 v6, v6, v78, -v110
	v_fma_f32 v7, v7, v78, -v111
	v_fma_f32 v16, v4, v78, -v94
	v_fma_f32 v17, v5, v78, -v95
	v_fma_f32 v0, v10, v78, -v98
	v_fma_f32 v1, v11, v78, -v99
	v_fma_f32 v2, v8, v78, -v92
	v_fma_f32 v3, v9, v78, -v93
	v_add_f32_e32 v78, v158, v159
	v_add_f32_e32 v78, v78, v156
	v_add_f32_e32 v78, v78, v157
	v_add_f32_e32 v78, v78, v168
	v_add_f32_e32 v78, v78, v169
	v_add_f32_e32 v78, v78, v166
	v_add_f32_e32 v78, v78, v167
	v_add_f32_e32 v78, v78, v172
	v_add_f32_e32 v78, v78, v173
	v_add_f32_e32 v78, v78, v170
	v_add_f32_e32 v78, v78, v171
	v_add_f32_e32 v78, v78, v180
	v_add_f32_e32 v78, v78, v181
	v_add_f32_e32 v78, v78, v174
	v_add_f32_e32 v78, v78, v175
	v_add_f32_e32 v78, v78, v200
	v_add_f32_e32 v78, v78, v201
	v_add_f32_e32 v78, v78, v182
	v_add_f32_e32 v78, v78, v183
	v_add_f32_e32 v78, v78, v204
	v_add_f32_e32 v78, v78, v205
	v_add_f32_e32 v78, v78, v202
	v_add_f32_e32 v78, v78, v203
	v_add_f32_e32 v78, v78, v212
	v_add_f32_e32 v78, v78, v213
	v_add_f32_e32 v78, v78, v206
	v_mul_f32_e32 v128, v44, v44
	v_mul_f32_e32 v129, v45, v45
	v_add_f32_e32 v78, v78, v207
	v_add_f32_e32 v78, v78, v128
	v_mul_f32_e32 v134, v46, v46
	v_mul_f32_e32 v135, v47, v47
	v_add_f32_e32 v78, v78, v129
	v_add_f32_e32 v78, v78, v134
	v_mul_f32_e32 v124, v40, v40
	v_mul_f32_e32 v125, v41, v41
	v_add_f32_e32 v78, v78, v135
	v_add_f32_e32 v78, v78, v124
	v_mul_f32_e32 v132, v38, v38
	v_mul_f32_e32 v133, v39, v39
	v_add_f32_e32 v78, v78, v125
	v_add_f32_e32 v78, v78, v132
	v_mul_f32_e32 v120, v36, v36
	v_mul_f32_e32 v121, v37, v37
	v_add_f32_e32 v78, v78, v133
	v_add_f32_e32 v78, v78, v120
	v_mul_f32_e32 v126, v34, v34
	v_mul_f32_e32 v127, v35, v35
	v_add_f32_e32 v78, v78, v121
	v_add_f32_e32 v78, v78, v126
	v_mul_f32_e32 v116, v32, v32
	v_mul_f32_e32 v117, v33, v33
	v_add_f32_e32 v78, v78, v127
	v_add_f32_e32 v78, v78, v116
	v_mul_f32_e32 v122, v26, v26
	v_mul_f32_e32 v123, v27, v27
	v_add_f32_e32 v78, v78, v117
	v_add_f32_e32 v78, v78, v122
	v_mul_f32_e32 v28, v24, v24
	v_mul_f32_e32 v29, v25, v25
	v_add_f32_e32 v78, v78, v123
	v_add_f32_e32 v28, v78, v28
	v_mul_f32_e32 v30, v22, v22
	v_mul_f32_e32 v31, v23, v23
	v_add_f32_e32 v28, v28, v29
	v_add_f32_e32 v28, v28, v30
	v_mul_f32_e32 v108, v20, v20
	v_mul_f32_e32 v109, v21, v21
	v_add_f32_e32 v28, v28, v31
	v_add_f32_e32 v28, v28, v108
	v_mul_f32_e32 v112, v18, v18
	v_mul_f32_e32 v113, v19, v19
	v_add_f32_e32 v28, v28, v109
	v_add_f32_e32 v28, v28, v112
	v_mul_f32_e32 v4, v16, v16
	v_mul_f32_e32 v5, v17, v17
	v_add_f32_e32 v28, v28, v113
	v_add_f32_e32 v4, v28, v4
	v_mul_f32_e32 v110, v6, v6
	v_mul_f32_e32 v111, v7, v7
	v_add_f32_e32 v4, v4, v5
	v_add_f32_e32 v4, v4, v110
	v_mul_f32_e32 v8, v2, v2
	v_mul_f32_e32 v9, v3, v3
	v_add_f32_e32 v4, v4, v111
	v_add_f32_e32 v4, v4, v8
	v_mul_f32_e32 v10, v0, v0
	v_mul_f32_e32 v11, v1, v1
	v_add_f32_e32 v4, v4, v9
	v_add_f32_e32 v4, v4, v10
	v_add_f32_e32 v4, v4, v11
	v_add_f32_e32 v4, v4, v136
	v_add_f32_e32 v4, v4, v137
	v_add_f32_e32 v4, v4, v138
	v_add_f32_e32 v8, v4, v139
	ds_bpermute_b32 v9, v151, v8
	v_add_f32_e32 v4, 1.0, v79
	v_add_f32_e32 v5, 1.0, v96
	v_rcp_f32_e32 v4, v4
	v_rcp_f32_e32 v5, v5
	s_waitcnt lgkmcnt(0)
	v_add_f32_e32 v8, v8, v9
	v_fmamk_f32 v8, v8, 0x3c000000, v198
	v_mul_f32_e32 v9, 0x4b800000, v8
	v_cmp_gt_f32_e32 vcc, s0, v8
	v_mul_f32_e32 v10, v4, v130
	v_mul_f32_e32 v11, v5, v131
	s_nop 0
	v_cndmask_b32_e32 v8, v8, v9, vcc
	v_rsq_f32_e32 v28, v8
	v_mul_f32_e32 v8, v210, v208
	v_mul_f32_e32 v9, v211, v209
	v_mul_f32_e32 v4, 0x45800000, v28
	v_cndmask_b32_e32 v4, v28, v4, vcc
	v_mul_f32_e32 v4, 0x3f4ccccd, v4
	v_mul_f32_e32 v28, v164, v4
	v_mul_f32_e32 v29, v165, v4
	s_waitcnt vmcnt(2)
	v_mul_f32_e32 v28, v72, v28
	v_mul_f32_e32 v29, v73, v29
	s_nop 0
	v_mul_f32_e32 v8, v8, v28
	v_mul_f32_e32 v9, v9, v29
	v_mul_f32_e32 v28, v178, v4
	v_mul_f32_e32 v29, v179, v4
	v_cvt_pk_bf16_f32 v8, v8, v9
	v_mul_f32_e32 v28, v74, v28
	v_mul_f32_e32 v29, v75, v29
	s_waitcnt vmcnt(1)
	v_lshlrev_b32_e32 v74, 16, v90
	v_mul_f32_e32 v10, v10, v28
	v_mul_f32_e32 v11, v11, v29
	v_and_b32_e32 v75, 0xffff0000, v90
	v_cvt_pk_bf16_f32 v9, v10, v11
	global_store_dwordx2 v[88:89], v[8:9], off offset:2048
	global_load_dwordx4 v[8:11], v[144:145], off offset:32
	s_nop 0
	global_load_dwordx2 v[28:29], v[76:77], off offset:32
	global_load_dwordx2 v[30:31], v[76:77], off offset:48
	global_load_dwordx2 v[72:73], v[76:77], off offset:64
	v_mul_f32_e32 v5, 0xbfb8aa3b, v74
	v_exp_f32_e32 v5, v5
	v_mul_f32_e32 v78, 0xbfb8aa3b, v75
	v_exp_f32_e32 v79, v78
	v_lshlrev_b32_e32 v88, 16, v91
	v_add_f32_e32 v5, 1.0, v5
	v_rcp_f32_e32 v78, v5
	v_add_f32_e32 v5, 1.0, v79
	v_and_b32_e32 v89, 0xffff0000, v91
	v_mul_f32_e32 v79, 0xbfb8aa3b, v88
	v_exp_f32_e32 v90, v79
	v_mul_f32_e32 v79, 0xbfb8aa3b, v89
	v_exp_f32_e32 v91, v79
	v_rcp_f32_e32 v79, v5
	v_add_f32_e32 v5, 1.0, v90
	v_rcp_f32_e32 v90, v5
	v_add_f32_e32 v5, 1.0, v91
	v_rcp_f32_e32 v91, v5
	v_mul_f32_e32 v74, v78, v74
	v_mul_f32_e32 v75, v79, v75
	v_mul_f32_e32 v78, v90, v88
	v_mul_f32_e32 v79, v91, v89
	v_mul_f32_e32 v88, v162, v4
	v_mul_f32_e32 v89, v163, v4
	s_waitcnt vmcnt(3)
	v_mul_f32_e32 v8, v8, v88
	v_mul_f32_e32 v9, v9, v89
	s_nop 0
	v_mul_f32_e32 v8, v74, v8
	v_mul_f32_e32 v9, v75, v9
	v_mul_f32_e32 v74, v176, v4
	v_mul_f32_e32 v75, v177, v4
	v_cvt_pk_bf16_f32 v8, v8, v9
	v_mul_f32_e32 v10, v10, v74
	v_mul_f32_e32 v11, v11, v75
	s_waitcnt vmcnt(2)
	v_lshlrev_b32_e32 v74, 16, v28
	v_mul_f32_e32 v10, v78, v10
	v_mul_f32_e32 v11, v79, v11
	v_and_b32_e32 v75, 0xffff0000, v28
	v_cvt_pk_bf16_f32 v9, v10, v11
	global_store_dwordx2 v[76:77], v[8:9], off offset:16
	global_load_dwordx4 v[8:11], v[144:145], off offset:64
	v_mul_f32_e32 v5, 0xbfb8aa3b, v74
	v_exp_f32_e32 v5, v5
	v_mul_f32_e32 v28, 0xbfb8aa3b, v75
	v_exp_f32_e32 v78, v28
	v_and_b32_e32 v79, 0xffff0000, v29
	v_add_f32_e32 v5, 1.0, v5
	v_rcp_f32_e32 v28, v5
	v_add_f32_e32 v5, 1.0, v78
	v_lshlrev_b32_e32 v78, 16, v29
	v_mul_f32_e32 v29, 0xbfb8aa3b, v78
	v_exp_f32_e32 v88, v29
	v_mul_f32_e32 v29, 0xbfb8aa3b, v79
	v_exp_f32_e32 v89, v29
	v_rcp_f32_e32 v29, v5
	v_add_f32_e32 v5, 1.0, v88
	v_rcp_f32_e32 v88, v5
	v_add_f32_e32 v5, 1.0, v89
	v_rcp_f32_e32 v89, v5
	v_mul_f32_e32 v28, v28, v74
	v_mul_f32_e32 v29, v29, v75
	v_mul_f32_e32 v74, v88, v78
	v_mul_f32_e32 v75, v89, v79
	v_mul_f32_e32 v78, v160, v4
	v_mul_f32_e32 v79, v161, v4
	s_waitcnt vmcnt(0)
	v_mul_f32_e32 v8, v8, v78
	v_mul_f32_e32 v9, v9, v79
	s_nop 0
	v_mul_f32_e32 v8, v8, v28
	v_mul_f32_e32 v9, v9, v29
	v_mul_f32_e32 v28, v58, v4
	v_mul_f32_e32 v29, v59, v4
	v_cvt_pk_bf16_f32 v8, v8, v9
	v_mul_f32_e32 v10, v10, v28
	v_mul_f32_e32 v11, v11, v29
	v_lshlrev_b32_e32 v28, 16, v30
	v_mul_f32_e32 v10, v10, v74
	v_mul_f32_e32 v11, v11, v75
	v_and_b32_e32 v29, 0xffff0000, v30
	v_cvt_pk_bf16_f32 v9, v10, v11
	global_store_dwordx2 v[76:77], v[8:9], off offset:32
	global_load_dwordx4 v[8:11], v[144:145], off offset:96
	v_lshlrev_b32_e32 v30, 16, v31
	v_and_b32_e32 v31, 0xffff0000, v31
	v_mul_f32_e32 v5, 0xbfb8aa3b, v28
	v_mul_f32_e32 v58, 0xbfb8aa3b, v29
	v_mul_f32_e32 v59, 0xbfb8aa3b, v30
	v_mul_f32_e32 v74, 0xbfb8aa3b, v31
	v_exp_f32_e32 v5, v5
	v_exp_f32_e32 v58, v58
	v_exp_f32_e32 v59, v59
	v_exp_f32_e32 v74, v74
	v_add_f32_e32 v5, 1.0, v5
	v_add_f32_e32 v75, 1.0, v58
	v_add_f32_e32 v78, 1.0, v59
	v_add_f32_e32 v79, 1.0, v74
	v_rcp_f32_e32 v58, v5
	v_rcp_f32_e32 v59, v75
	v_rcp_f32_e32 v74, v78
	v_rcp_f32_e32 v75, v79
	v_mul_f32_e32 v60, v60, v4
	v_mul_f32_e32 v61, v61, v4
	v_mul_f32_e32 v62, v62, v4
	v_mul_f32_e32 v63, v63, v4
	v_mul_f32_e32 v28, v58, v28
	v_mul_f32_e32 v29, v59, v29
	v_mul_f32_e32 v30, v74, v30
	v_mul_f32_e32 v31, v75, v31
	v_lshlrev_b32_e32 v58, 16, v73
	v_and_b32_e32 v59, 0xffff0000, v73
	s_waitcnt vmcnt(0)
	v_mul_f32_e32 v8, v8, v60
	v_mul_f32_e32 v9, v9, v61
	v_mul_f32_e32 v10, v10, v62
	v_mul_f32_e32 v11, v11, v63
	v_mul_f32_e32 v8, v8, v28
	v_mul_f32_e32 v9, v9, v29
	v_mul_f32_e32 v10, v10, v30
	v_mul_f32_e32 v11, v11, v31
	v_cvt_pk_bf16_f32 v8, v8, v9
	v_cvt_pk_bf16_f32 v9, v10, v11
	global_store_dwordx2 v[76:77], v[8:9], off offset:48
	global_load_dwordx4 v[8:11], v[144:145], off offset:128
	s_nop 0
	global_load_dwordx2 v[28:29], v[76:77], off offset:80
	v_lshlrev_b32_e32 v30, 16, v72
	v_and_b32_e32 v31, 0xffff0000, v72
	v_mul_f32_e32 v5, 0xbfb8aa3b, v30
	v_mul_f32_e32 v60, 0xbfb8aa3b, v31
	v_mul_f32_e32 v61, 0xbfb8aa3b, v58
	v_mul_f32_e32 v62, 0xbfb8aa3b, v59
	v_exp_f32_e32 v5, v5
	v_exp_f32_e32 v60, v60
	v_exp_f32_e32 v61, v61
	v_exp_f32_e32 v62, v62
	v_add_f32_e32 v5, 1.0, v5
	v_add_f32_e32 v63, 1.0, v60
	v_add_f32_e32 v72, 1.0, v61
	v_add_f32_e32 v73, 1.0, v62
	v_rcp_f32_e32 v60, v5
	v_rcp_f32_e32 v61, v63
	v_rcp_f32_e32 v62, v72
	v_rcp_f32_e32 v63, v73
	v_mul_f32_e32 v56, v56, v4
	v_mul_f32_e32 v57, v57, v4
	v_mul_f32_e32 v54, v54, v4
	v_mul_f32_e32 v55, v55, v4
	v_mul_f32_e32 v30, v60, v30
	v_mul_f32_e32 v31, v61, v31
	v_mul_f32_e32 v58, v62, v58
	v_mul_f32_e32 v59, v63, v59
	s_waitcnt vmcnt(1)
	v_mul_f32_e32 v8, v56, v8
	v_mul_f32_e32 v9, v57, v9
	v_mul_f32_e32 v10, v54, v10
	v_mul_f32_e32 v11, v55, v11
	v_mul_f32_e32 v8, v8, v30
	v_mul_f32_e32 v9, v9, v31
	v_mul_f32_e32 v10, v10, v58
	v_mul_f32_e32 v11, v11, v59
	v_cvt_pk_bf16_f32 v8, v8, v9
	v_cvt_pk_bf16_f32 v9, v10, v11
	global_store_dwordx2 v[76:77], v[8:9], off offset:64
	global_load_dwordx4 v[8:11], v[144:145], off offset:160
	s_nop 0
	global_load_dwordx2 v[30:31], v[76:77], off offset:96
	global_load_dwordx2 v[54:55], v[76:77], off offset:112
	global_load_dwordx2 v[56:57], v[76:77], off offset:128
	s_waitcnt vmcnt(5)
	v_lshlrev_b32_e32 v58, 16, v28
	v_and_b32_e32 v59, 0xffff0000, v28
	v_lshlrev_b32_e32 v28, 16, v29
	v_and_b32_e32 v29, 0xffff0000, v29
	v_mul_f32_e32 v5, 0xbfb8aa3b, v58
	v_mul_f32_e32 v60, 0xbfb8aa3b, v59
	v_mul_f32_e32 v61, 0xbfb8aa3b, v28
	v_mul_f32_e32 v62, 0xbfb8aa3b, v29
	v_exp_f32_e32 v5, v5
	v_exp_f32_e32 v60, v60
	v_exp_f32_e32 v61, v61
	v_exp_f32_e32 v62, v62
	v_add_f32_e32 v5, 1.0, v5
	v_add_f32_e32 v63, 1.0, v60
	v_add_f32_e32 v72, 1.0, v61
	v_add_f32_e32 v73, 1.0, v62
	v_rcp_f32_e32 v60, v5
	v_rcp_f32_e32 v61, v63
	v_rcp_f32_e32 v62, v72
	v_rcp_f32_e32 v63, v73
	v_mul_f32_e32 v52, v52, v4
	v_mul_f32_e32 v53, v53, v4
	v_mul_f32_e32 v50, v50, v4
	v_mul_f32_e32 v51, v51, v4
	v_mul_f32_e32 v58, v60, v58
	v_mul_f32_e32 v59, v61, v59
	v_mul_f32_e32 v28, v62, v28
	v_mul_f32_e32 v29, v63, v29
	s_waitcnt vmcnt(3)
	v_mul_f32_e32 v8, v52, v8
	v_mul_f32_e32 v9, v53, v9
	v_mul_f32_e32 v10, v50, v10
	v_mul_f32_e32 v11, v51, v11
	v_mul_f32_e32 v8, v8, v58
	v_mul_f32_e32 v9, v9, v59
	v_mul_f32_e32 v10, v10, v28
	v_mul_f32_e32 v11, v11, v29
	v_cvt_pk_bf16_f32 v8, v8, v9
	v_cvt_pk_bf16_f32 v9, v10, v11
	global_store_dwordx2 v[76:77], v[8:9], off offset:80
	global_load_dwordx4 v[8:11], v[144:145], off offset:192
	s_waitcnt vmcnt(4)
	v_lshlrev_b32_e32 v28, 16, v30
	v_and_b32_e32 v29, 0xffff0000, v30
	v_lshlrev_b32_e32 v30, 16, v31
	v_and_b32_e32 v31, 0xffff0000, v31
	v_mul_f32_e32 v5, 0xbfb8aa3b, v28
	v_mul_f32_e32 v50, 0xbfb8aa3b, v29
	v_mul_f32_e32 v51, 0xbfb8aa3b, v30
	v_mul_f32_e32 v52, 0xbfb8aa3b, v31
	v_exp_f32_e32 v5, v5
	v_exp_f32_e32 v50, v50
	v_exp_f32_e32 v51, v51
	v_exp_f32_e32 v52, v52
	v_add_f32_e32 v5, 1.0, v5
	v_add_f32_e32 v53, 1.0, v50
	v_add_f32_e32 v58, 1.0, v51
	v_add_f32_e32 v59, 1.0, v52
	v_rcp_f32_e32 v50, v5
	v_rcp_f32_e32 v51, v53
	v_rcp_f32_e32 v52, v58
	v_rcp_f32_e32 v53, v59
	v_mul_f32_e32 v48, v48, v4
	v_mul_f32_e32 v49, v49, v4
	v_mul_f32_e32 v42, v42, v4
	v_mul_f32_e32 v43, v43, v4
	v_mul_f32_e32 v28, v50, v28
	v_mul_f32_e32 v29, v51, v29
	v_mul_f32_e32 v30, v52, v30
	v_mul_f32_e32 v31, v53, v31
	s_waitcnt vmcnt(0)
	v_mul_f32_e32 v8, v48, v8
	v_mul_f32_e32 v9, v49, v9
	v_mul_f32_e32 v10, v42, v10
	v_mul_f32_e32 v11, v43, v11
	v_mul_f32_e32 v8, v8, v28
	v_mul_f32_e32 v9, v9, v29
	v_mul_f32_e32 v10, v10, v30
	v_mul_f32_e32 v11, v11, v31
	v_cvt_pk_bf16_f32 v8, v8, v9
	v_cvt_pk_bf16_f32 v9, v10, v11
	global_store_dwordx2 v[76:77], v[8:9], off offset:96
	global_load_dwordx4 v[8:11], v[144:145], off offset:224
	v_lshlrev_b32_e32 v28, 16, v54
	v_and_b32_e32 v29, 0xffff0000, v54
	v_lshlrev_b32_e32 v30, 16, v55
	v_and_b32_e32 v31, 0xffff0000, v55
	v_mul_f32_e32 v5, 0xbfb8aa3b, v28
	v_mul_f32_e32 v42, 0xbfb8aa3b, v29
	v_mul_f32_e32 v43, 0xbfb8aa3b, v30
	v_mul_f32_e32 v48, 0xbfb8aa3b, v31
	v_exp_f32_e32 v5, v5
	v_exp_f32_e32 v42, v42
	v_exp_f32_e32 v43, v43
	v_exp_f32_e32 v48, v48
	v_add_f32_e32 v5, 1.0, v5
	v_add_f32_e32 v49, 1.0, v42
	v_add_f32_e32 v50, 1.0, v43
	v_add_f32_e32 v51, 1.0, v48
	v_rcp_f32_e32 v42, v5
	v_rcp_f32_e32 v43, v49
	v_rcp_f32_e32 v48, v50
	v_rcp_f32_e32 v49, v51
	v_mul_f32_e32 v44, v44, v4
	v_mul_f32_e32 v45, v45, v4
	v_mul_f32_e32 v46, v46, v4
	v_mul_f32_e32 v47, v47, v4
	v_mul_f32_e32 v28, v42, v28
	v_mul_f32_e32 v29, v43, v29
	v_mul_f32_e32 v30, v48, v30
	v_mul_f32_e32 v31, v49, v31
	v_lshlrev_b32_e32 v42, 16, v57
	v_and_b32_e32 v43, 0xffff0000, v57
	s_waitcnt vmcnt(0)
	v_mul_f32_e32 v8, v44, v8
	v_mul_f32_e32 v9, v45, v9
	v_mul_f32_e32 v10, v46, v10
	v_mul_f32_e32 v11, v47, v11
	v_mul_f32_e32 v8, v8, v28
	v_mul_f32_e32 v9, v9, v29
	v_mul_f32_e32 v10, v10, v30
	v_mul_f32_e32 v11, v11, v31
	v_cvt_pk_bf16_f32 v8, v8, v9
	v_cvt_pk_bf16_f32 v9, v10, v11
	global_store_dwordx2 v[76:77], v[8:9], off offset:112
	global_load_dwordx4 v[8:11], v[144:145], off offset:256
	s_nop 0
	global_load_dwordx2 v[28:29], v[76:77], off offset:144
	v_lshlrev_b32_e32 v30, 16, v56
	v_and_b32_e32 v31, 0xffff0000, v56
	v_mul_f32_e32 v5, 0xbfb8aa3b, v30
	v_mul_f32_e32 v44, 0xbfb8aa3b, v31
	v_mul_f32_e32 v45, 0xbfb8aa3b, v42
	v_mul_f32_e32 v46, 0xbfb8aa3b, v43
	v_exp_f32_e32 v5, v5
	v_exp_f32_e32 v44, v44
	v_exp_f32_e32 v45, v45
	v_exp_f32_e32 v46, v46
	v_add_f32_e32 v5, 1.0, v5
	v_add_f32_e32 v47, 1.0, v44
	v_add_f32_e32 v48, 1.0, v45
	v_add_f32_e32 v49, 1.0, v46
	v_rcp_f32_e32 v44, v5
	v_rcp_f32_e32 v45, v47
	v_rcp_f32_e32 v46, v48
	v_rcp_f32_e32 v47, v49
	v_mul_f32_e32 v40, v40, v4
	v_mul_f32_e32 v41, v41, v4
	v_mul_f32_e32 v38, v38, v4
	v_mul_f32_e32 v39, v39, v4
	v_mul_f32_e32 v30, v44, v30
	v_mul_f32_e32 v31, v45, v31
	v_mul_f32_e32 v42, v46, v42
	v_mul_f32_e32 v43, v47, v43
	s_waitcnt vmcnt(1)
	v_mul_f32_e32 v8, v40, v8
	v_mul_f32_e32 v9, v41, v9
	v_mul_f32_e32 v10, v38, v10
	v_mul_f32_e32 v11, v39, v11
	v_mul_f32_e32 v8, v8, v30
	v_mul_f32_e32 v9, v9, v31
	v_mul_f32_e32 v10, v10, v42
	v_mul_f32_e32 v11, v11, v43
	v_cvt_pk_bf16_f32 v8, v8, v9
	v_cvt_pk_bf16_f32 v9, v10, v11
	global_store_dwordx2 v[76:77], v[8:9], off offset:128
	global_load_dwordx4 v[8:11], v[144:145], off offset:288
	s_nop 0
	global_load_dwordx2 v[30:31], v[76:77], off offset:160
	global_load_dwordx2 v[38:39], v[76:77], off offset:176
	global_load_dwordx2 v[40:41], v[76:77], off offset:192
	s_waitcnt vmcnt(5)
	v_lshlrev_b32_e32 v42, 16, v28
	v_and_b32_e32 v43, 0xffff0000, v28
	v_lshlrev_b32_e32 v28, 16, v29
	v_and_b32_e32 v29, 0xffff0000, v29
	v_mul_f32_e32 v5, 0xbfb8aa3b, v42
	v_mul_f32_e32 v44, 0xbfb8aa3b, v43
	v_mul_f32_e32 v45, 0xbfb8aa3b, v28
	v_mul_f32_e32 v46, 0xbfb8aa3b, v29
	v_exp_f32_e32 v5, v5
	v_exp_f32_e32 v44, v44
	v_exp_f32_e32 v45, v45
	v_exp_f32_e32 v46, v46
	v_add_f32_e32 v5, 1.0, v5
	v_add_f32_e32 v47, 1.0, v44
	v_add_f32_e32 v48, 1.0, v45
	v_add_f32_e32 v49, 1.0, v46
	v_rcp_f32_e32 v44, v5
	v_rcp_f32_e32 v45, v47
	v_rcp_f32_e32 v46, v48
	v_rcp_f32_e32 v47, v49
	v_mul_f32_e32 v36, v36, v4
	v_mul_f32_e32 v37, v37, v4
	v_mul_f32_e32 v34, v34, v4
	v_mul_f32_e32 v35, v35, v4
	v_mul_f32_e32 v42, v44, v42
	v_mul_f32_e32 v43, v45, v43
	v_mul_f32_e32 v28, v46, v28
	v_mul_f32_e32 v29, v47, v29
	s_waitcnt vmcnt(3)
	v_mul_f32_e32 v8, v36, v8
	v_mul_f32_e32 v9, v37, v9
	v_mul_f32_e32 v10, v34, v10
	v_mul_f32_e32 v11, v35, v11
	v_mul_f32_e32 v8, v8, v42
	v_mul_f32_e32 v9, v9, v43
	v_mul_f32_e32 v10, v10, v28
	v_mul_f32_e32 v11, v11, v29
	v_cvt_pk_bf16_f32 v8, v8, v9
	v_cvt_pk_bf16_f32 v9, v10, v11
	global_store_dwordx2 v[76:77], v[8:9], off offset:144
	global_load_dwordx4 v[8:11], v[144:145], off offset:320
	s_waitcnt vmcnt(4)
	v_lshlrev_b32_e32 v28, 16, v30
	v_and_b32_e32 v29, 0xffff0000, v30
	v_lshlrev_b32_e32 v30, 16, v31
	v_and_b32_e32 v31, 0xffff0000, v31
	v_mul_f32_e32 v5, 0xbfb8aa3b, v28
	v_mul_f32_e32 v34, 0xbfb8aa3b, v29
	v_mul_f32_e32 v35, 0xbfb8aa3b, v30
	v_mul_f32_e32 v36, 0xbfb8aa3b, v31
	v_exp_f32_e32 v5, v5
	v_exp_f32_e32 v34, v34
	v_exp_f32_e32 v35, v35
	v_exp_f32_e32 v36, v36
	v_add_f32_e32 v5, 1.0, v5
	v_add_f32_e32 v37, 1.0, v34
	v_add_f32_e32 v42, 1.0, v35
	v_add_f32_e32 v43, 1.0, v36
	v_rcp_f32_e32 v34, v5
	v_rcp_f32_e32 v35, v37
	v_rcp_f32_e32 v36, v42
	v_rcp_f32_e32 v37, v43
	v_mul_f32_e32 v32, v32, v4
	v_mul_f32_e32 v33, v33, v4
	v_mul_f32_e32 v26, v26, v4
	v_mul_f32_e32 v27, v27, v4
	v_mul_f32_e32 v28, v34, v28
	v_mul_f32_e32 v29, v35, v29
	v_mul_f32_e32 v30, v36, v30
	v_mul_f32_e32 v31, v37, v31
	s_waitcnt vmcnt(0)
	v_mul_f32_e32 v8, v32, v8
	v_mul_f32_e32 v9, v33, v9
	v_mul_f32_e32 v10, v26, v10
	v_mul_f32_e32 v11, v27, v11
	v_mul_f32_e32 v8, v8, v28
	v_mul_f32_e32 v9, v9, v29
	v_mul_f32_e32 v10, v10, v30
	v_mul_f32_e32 v11, v11, v31
	v_cvt_pk_bf16_f32 v8, v8, v9
	v_cvt_pk_bf16_f32 v9, v10, v11
	global_store_dwordx2 v[76:77], v[8:9], off offset:160
	global_load_dwordx4 v[8:11], v[144:145], off offset:352
	v_lshlrev_b32_e32 v26, 16, v38
	v_and_b32_e32 v27, 0xffff0000, v38
	v_lshlrev_b32_e32 v28, 16, v39
	v_and_b32_e32 v29, 0xffff0000, v39
	v_mul_f32_e32 v5, 0xbfb8aa3b, v26
	v_mul_f32_e32 v30, 0xbfb8aa3b, v27
	v_mul_f32_e32 v31, 0xbfb8aa3b, v28
	v_mul_f32_e32 v32, 0xbfb8aa3b, v29
	v_exp_f32_e32 v5, v5
	v_exp_f32_e32 v30, v30
	v_exp_f32_e32 v31, v31
	v_exp_f32_e32 v32, v32
	v_add_f32_e32 v5, 1.0, v5
	v_add_f32_e32 v33, 1.0, v30
	v_add_f32_e32 v34, 1.0, v31
	v_add_f32_e32 v35, 1.0, v32
	v_rcp_f32_e32 v30, v5
	v_rcp_f32_e32 v31, v33
	v_rcp_f32_e32 v32, v34
	v_rcp_f32_e32 v33, v35
	v_mul_f32_e32 v24, v24, v4
	v_mul_f32_e32 v25, v25, v4
	v_mul_f32_e32 v22, v22, v4
	v_mul_f32_e32 v23, v23, v4
	v_mul_f32_e32 v26, v30, v26
	v_mul_f32_e32 v27, v31, v27
	v_mul_f32_e32 v28, v32, v28
	v_mul_f32_e32 v29, v33, v29
	s_waitcnt vmcnt(0)
	v_mul_f32_e32 v8, v24, v8
	v_mul_f32_e32 v9, v25, v9
	v_mul_f32_e32 v10, v22, v10
	v_mul_f32_e32 v11, v23, v11
	v_mul_f32_e32 v8, v8, v26
	v_mul_f32_e32 v9, v9, v27
	v_mul_f32_e32 v10, v10, v28
	v_mul_f32_e32 v11, v11, v29
	v_cvt_pk_bf16_f32 v8, v8, v9
	v_cvt_pk_bf16_f32 v9, v10, v11
	global_store_dwordx2 v[76:77], v[8:9], off offset:176
	global_load_dwordx4 v[8:11], v[144:145], off offset:384
	s_nop 0
	global_load_dwordx2 v[22:23], v[76:77], off offset:208
	v_lshlrev_b32_e32 v24, 16, v40
	v_and_b32_e32 v25, 0xffff0000, v40
	v_lshlrev_b32_e32 v26, 16, v41
	v_and_b32_e32 v27, 0xffff0000, v41
	v_mul_f32_e32 v5, 0xbfb8aa3b, v24
	v_mul_f32_e32 v28, 0xbfb8aa3b, v25
	v_mul_f32_e32 v29, 0xbfb8aa3b, v26
	v_mul_f32_e32 v30, 0xbfb8aa3b, v27
	v_exp_f32_e32 v5, v5
	v_exp_f32_e32 v28, v28
	v_exp_f32_e32 v29, v29
	v_exp_f32_e32 v30, v30
	v_add_f32_e32 v5, 1.0, v5
	v_add_f32_e32 v31, 1.0, v28
	v_add_f32_e32 v32, 1.0, v29
	v_add_f32_e32 v33, 1.0, v30
	v_rcp_f32_e32 v28, v5
	v_rcp_f32_e32 v29, v31
	v_rcp_f32_e32 v30, v32
	v_rcp_f32_e32 v31, v33
	v_mul_f32_e32 v20, v20, v4
	v_mul_f32_e32 v21, v21, v4
	v_mul_f32_e32 v18, v18, v4
	v_mul_f32_e32 v19, v19, v4
	v_mul_f32_e32 v24, v28, v24
	v_mul_f32_e32 v25, v29, v25
	v_mul_f32_e32 v26, v30, v26
	v_mul_f32_e32 v27, v31, v27
	s_waitcnt vmcnt(1)
	v_mul_f32_e32 v8, v20, v8
	v_mul_f32_e32 v9, v21, v9
	v_mul_f32_e32 v10, v18, v10
	v_mul_f32_e32 v11, v19, v11
	v_mul_f32_e32 v8, v8, v24
	v_mul_f32_e32 v9, v9, v25
	v_mul_f32_e32 v10, v10, v26
	v_mul_f32_e32 v11, v11, v27
	v_cvt_pk_bf16_f32 v8, v8, v9
	v_cvt_pk_bf16_f32 v9, v10, v11
	global_store_dwordx2 v[76:77], v[8:9], off offset:192
	global_load_dwordx4 v[8:11], v[144:145], off offset:416
	s_nop 0
	global_load_dwordx2 v[18:19], v[76:77], off offset:224
	s_waitcnt vmcnt(3)
	v_lshlrev_b32_e32 v20, 16, v22
	v_and_b32_e32 v21, 0xffff0000, v22
	v_lshlrev_b32_e32 v22, 16, v23
	v_and_b32_e32 v23, 0xffff0000, v23
	v_mul_f32_e32 v5, 0xbfb8aa3b, v20
	v_mul_f32_e32 v24, 0xbfb8aa3b, v21
	v_mul_f32_e32 v25, 0xbfb8aa3b, v22
	v_mul_f32_e32 v26, 0xbfb8aa3b, v23
	v_exp_f32_e32 v5, v5
	v_exp_f32_e32 v24, v24
	v_exp_f32_e32 v25, v25
	v_exp_f32_e32 v26, v26
	v_add_f32_e32 v5, 1.0, v5
	v_add_f32_e32 v27, 1.0, v24
	v_add_f32_e32 v28, 1.0, v25
	v_add_f32_e32 v29, 1.0, v26
	v_rcp_f32_e32 v24, v5
	v_rcp_f32_e32 v25, v27
	v_rcp_f32_e32 v26, v28
	v_rcp_f32_e32 v27, v29
	v_mul_f32_e32 v16, v16, v4
	v_mul_f32_e32 v17, v17, v4
	v_mul_f32_e32 v6, v6, v4
	v_mul_f32_e32 v7, v7, v4
	v_mul_f32_e32 v20, v24, v20
	v_mul_f32_e32 v21, v25, v21
	v_mul_f32_e32 v22, v26, v22
	v_mul_f32_e32 v23, v27, v23
	s_waitcnt vmcnt(1)
	v_mul_f32_e32 v8, v16, v8
	v_mul_f32_e32 v9, v17, v9
	v_mul_f32_e32 v6, v6, v10
	v_mul_f32_e32 v7, v7, v11
	v_mul_f32_e32 v8, v8, v20
	v_mul_f32_e32 v9, v9, v21
	v_mul_f32_e32 v6, v6, v22
	v_mul_f32_e32 v7, v7, v23
	v_cvt_pk_bf16_f32 v8, v8, v9
	v_cvt_pk_bf16_f32 v9, v6, v7
	global_store_dwordx2 v[76:77], v[8:9], off offset:208
	global_load_dwordx4 v[6:9], v[144:145], off offset:448
	s_waitcnt vmcnt(2)
	v_lshlrev_b32_e32 v10, 16, v18
	v_and_b32_e32 v11, 0xffff0000, v18
	v_lshlrev_b32_e32 v16, 16, v19
	v_and_b32_e32 v17, 0xffff0000, v19
	v_mul_f32_e32 v5, 0xbfb8aa3b, v10
	v_mul_f32_e32 v18, 0xbfb8aa3b, v11
	v_mul_f32_e32 v19, 0xbfb8aa3b, v16
	v_mul_f32_e32 v20, 0xbfb8aa3b, v17
	v_exp_f32_e32 v5, v5
	v_exp_f32_e32 v18, v18
	v_exp_f32_e32 v19, v19
	v_exp_f32_e32 v20, v20
	v_add_f32_e32 v5, 1.0, v5
	v_add_f32_e32 v21, 1.0, v18
	v_add_f32_e32 v22, 1.0, v19
	v_add_f32_e32 v23, 1.0, v20
	v_rcp_f32_e32 v18, v5
	v_rcp_f32_e32 v19, v21
	v_rcp_f32_e32 v20, v22
	v_rcp_f32_e32 v21, v23
	v_mul_f32_e32 v2, v2, v4
	v_mul_f32_e32 v3, v3, v4
	v_mul_f32_e32 v0, v0, v4
	v_mul_f32_e32 v1, v1, v4
	v_mul_f32_e32 v10, v18, v10
	v_mul_f32_e32 v11, v19, v11
	v_mul_f32_e32 v16, v20, v16
	v_mul_f32_e32 v17, v21, v17
	s_waitcnt vmcnt(0)
	v_mul_f32_e32 v2, v2, v6
	v_mul_f32_e32 v3, v3, v7
	v_mul_f32_e32 v0, v0, v8
	v_mul_f32_e32 v1, v1, v9
	v_mul_f32_e32 v2, v2, v10
	v_mul_f32_e32 v3, v3, v11
	v_mul_f32_e32 v0, v0, v16
	v_mul_f32_e32 v1, v1, v17
	v_cvt_pk_bf16_f32 v2, v2, v3
	v_cvt_pk_bf16_f32 v3, v0, v1
	global_store_dwordx2 v[76:77], v[2:3], off offset:224
	global_load_dwordx4 v[0:3], v[144:145], off offset:480
	v_lshlrev_b32_e32 v6, 16, v184
	v_and_b32_e32 v7, 0xffff0000, v184
	v_lshlrev_b32_e32 v8, 16, v185
	v_and_b32_e32 v9, 0xffff0000, v185
	v_mul_f32_e32 v5, 0xbfb8aa3b, v6
	v_mul_f32_e32 v10, 0xbfb8aa3b, v7
	v_mul_f32_e32 v11, 0xbfb8aa3b, v8
	v_mul_f32_e32 v16, 0xbfb8aa3b, v9
	v_exp_f32_e32 v5, v5
	v_exp_f32_e32 v10, v10
	v_exp_f32_e32 v11, v11
	v_exp_f32_e32 v16, v16
	v_add_f32_e32 v5, 1.0, v5
	v_add_f32_e32 v17, 1.0, v10
	v_add_f32_e32 v18, 1.0, v11
	v_add_f32_e32 v19, 1.0, v16
	v_rcp_f32_e32 v10, v5
	v_rcp_f32_e32 v11, v17
	v_rcp_f32_e32 v16, v18
	v_rcp_f32_e32 v17, v19
	v_mul_f32_e32 v12, v12, v4
	v_mul_f32_e32 v13, v13, v4
	v_mul_f32_e32 v5, v15, v4
	v_mul_f32_e32 v4, v14, v4
	v_mul_f32_e32 v6, v10, v6
	v_mul_f32_e32 v7, v11, v7
	v_mul_f32_e32 v8, v16, v8
	v_mul_f32_e32 v9, v17, v9
	s_waitcnt vmcnt(0)
	v_mul_f32_e32 v0, v12, v0
	v_mul_f32_e32 v1, v13, v1
	v_mul_f32_e32 v2, v4, v2
	v_mul_f32_e32 v3, v5, v3
	v_mul_f32_e32 v0, v0, v6
	v_mul_f32_e32 v1, v1, v7
	v_mul_f32_e32 v2, v2, v8
	v_mul_f32_e32 v3, v3, v9
	v_cvt_pk_bf16_f32 v0, v0, v1
	v_cvt_pk_bf16_f32 v1, v2, v3
	global_store_dwordx2 v[76:77], v[0:1], off offset:240
	s_branch .LBB0_229

.LBB0_333:
	s_lshl_b32 s10, s50, 8
	s_and_b32 s11, s50, -4
	s_cmp_eq_u32 s11, 4
	s_cselect_b64 vcc, -1, 0
	s_cmp_gt_i32 s50, 15
	v_or_b32_e32 v156, s10, v146
	s_cselect_b64 s[38:39], -1, 0
	s_addk_i32 s10, 0xfc00
	s_lshr_b32 s10, s10, 8
	v_cvt_f32_u32_e32 v158, s10
	v_ashrrev_i32_e32 v157, 31, v156
	v_lshl_add_u32 v164, s36, 8, v144
	v_cndmask_b32_e64 v157, v157, 0, s[38:39]
	v_sub_f32_e32 v158, 0xc0a00000, v158
	v_cmp_gt_f32_e64 s[10:11], s48, v158
	s_nop 1
	v_cndmask_b32_e64 v159, 0, v154, s[10:11]
	v_add_f32_e32 v158, v158, v159
	v_exp_f32_e32 v158, v158
	s_and_b64 s[10:11], s[10:11], exec
	s_cselect_b32 s10, 0xffffffc0, 0
	v_ldexp_f32 v158, v158, s10
	v_sub_f32_e32 v158, 1.0, v158
	v_log_f32_e32 v159, v158
	s_nop 0
	v_mul_f32_e32 v158, v159, v147
	v_cmp_gt_f32_e64 s[10:11], s48, v158
	s_nop 1
	v_cndmask_b32_e64 v158, 0, v154, s[10:11]
	v_fmac_f32_e32 v158, v159, v147
	v_exp_f32_e32 v158, v158
	v_cndmask_b32_e64 v160, 0, v155, s[10:11]
	v_ldexp_f32 v158, v158, v160
	v_mul_f32_e32 v158, 0x3d800000, v158
	v_cndmask_b32_e32 v158, 1.0, v158, vcc
	v_mul_f32_e32 v124, v158, v124
	v_mul_f32_e32 v125, v158, v125
	v_mul_f32_e32 v126, v158, v126
	v_mul_f32_e32 v127, v158, v127
	v_mul_f32_e32 v120, v158, v120
	v_mul_f32_e32 v121, v158, v121
	v_cvt_pk_bf16_f32 v124, v124, v125
	v_cvt_pk_bf16_f32 v125, v126, v127
	v_cvt_pk_bf16_f32 v126, v120, v121
	v_mul_f32_e32 v120, v158, v122
	v_mul_f32_e32 v121, v158, v123
	v_cvt_pk_bf16_f32 v127, v120, v121
	v_mov_b64_e32 v[120:121], s[62:63]
	v_mad_i64_i32 v[160:161], s[10:11], v164, s49, v[120:121]
	v_lshlrev_b64 v[122:123], 1, v[156:157]
	v_lshl_add_u64 v[162:163], v[160:161], 0, v[122:123]
	v_mul_f32_e32 v116, v158, v116
	v_mul_f32_e32 v117, v158, v117
	v_mul_f32_e32 v118, v158, v118
	v_mul_f32_e32 v119, v158, v119
	v_mul_f32_e32 v112, v158, v112
	v_mul_f32_e32 v113, v158, v113
	global_store_dwordx4 v[162:163], v[124:127], off
	v_cvt_pk_bf16_f32 v116, v116, v117
	v_cvt_pk_bf16_f32 v117, v118, v119
	v_or_b32_e32 v124, 0x80, v156
	v_cvt_pk_bf16_f32 v118, v112, v113
	v_mul_f32_e32 v112, v158, v114
	v_mul_f32_e32 v113, v158, v115
	v_cvt_pk_bf16_f32 v119, v112, v113
	v_ashrrev_i32_e32 v112, 31, v124
	v_cndmask_b32_e64 v125, v112, 0, s[38:39]
	v_lshlrev_b64 v[112:113], 1, v[124:125]
	v_mul_f32_e32 v124, v159, v148
	v_cmp_gt_f32_e64 s[10:11], s48, v124
	v_lshl_add_u64 v[114:115], v[160:161], 0, v[112:113]
	global_store_dwordx4 v[114:115], v[116:119], off
	v_cndmask_b32_e64 v124, 0, v154, s[10:11]
	v_fmac_f32_e32 v124, v159, v148
	v_exp_f32_e32 v124, v124
	v_cndmask_b32_e64 v114, 0, v155, s[10:11]
	v_or_b32_e32 v115, 16, v164
	v_mul_f32_e32 v60, v158, v60
	v_mul_f32_e32 v61, v158, v61
	v_ldexp_f32 v114, v124, v114
	v_mul_f32_e32 v114, 0x3d800000, v114
	v_cndmask_b32_e32 v114, 1.0, v114, vcc
	v_mul_f32_e32 v108, v114, v108
	v_mul_f32_e32 v109, v114, v109
	v_mul_f32_e32 v110, v114, v110
	v_mul_f32_e32 v111, v114, v111
	v_mul_f32_e32 v104, v114, v104
	v_mul_f32_e32 v105, v114, v105
	v_cvt_pk_bf16_f32 v108, v108, v109
	v_cvt_pk_bf16_f32 v109, v110, v111
	v_cvt_pk_bf16_f32 v110, v104, v105
	v_mul_f32_e32 v104, v114, v106
	v_mul_f32_e32 v105, v114, v107
	v_mul_f32_e32 v100, v114, v100
	v_mul_f32_e32 v101, v114, v101
	v_mul_f32_e32 v102, v114, v102
	v_mul_f32_e32 v103, v114, v103
	v_mul_f32_e32 v92, v114, v92
	v_mul_f32_e32 v93, v114, v93
	v_cvt_pk_bf16_f32 v111, v104, v105
	v_mad_i64_i32 v[104:105], s[10:11], v115, s49, v[120:121]
	v_cvt_pk_bf16_f32 v100, v100, v101
	v_cvt_pk_bf16_f32 v101, v102, v103
	v_cvt_pk_bf16_f32 v102, v92, v93
	v_mul_f32_e32 v92, v114, v94
	v_mul_f32_e32 v93, v114, v95
	v_mul_f32_e32 v94, v159, v149
	v_cmp_gt_f32_e64 s[10:11], s48, v94
	v_lshl_add_u64 v[106:107], v[104:105], 0, v[122:123]
	v_cvt_pk_bf16_f32 v103, v92, v93
	v_cndmask_b32_e64 v94, 0, v154, s[10:11]
	v_fmac_f32_e32 v94, v159, v149
	v_exp_f32_e32 v94, v94
	v_lshl_add_u64 v[92:93], v[104:105], 0, v[112:113]
	global_store_dwordx4 v[106:107], v[108:111], off
	global_store_dwordx4 v[92:93], v[100:103], off
	v_cndmask_b32_e64 v92, 0, v155, s[10:11]
	v_ldexp_f32 v92, v94, v92
	v_mul_f32_e32 v92, 0x3d800000, v92
	v_or_b32_e32 v101, 32, v164
	v_cndmask_b32_e32 v100, 1.0, v92, vcc
	v_mul_f32_e32 v92, v100, v96
	v_mul_f32_e32 v93, v100, v97
	v_mul_f32_e32 v94, v100, v98
	v_mul_f32_e32 v95, v100, v99
	v_mul_f32_e32 v88, v100, v88
	v_mul_f32_e32 v89, v100, v89
	v_cvt_pk_bf16_f32 v92, v92, v93
	v_cvt_pk_bf16_f32 v93, v94, v95
	v_cvt_pk_bf16_f32 v94, v88, v89
	v_mul_f32_e32 v88, v100, v90
	v_mul_f32_e32 v89, v100, v91
	v_mul_f32_e32 v84, v100, v84
	v_mul_f32_e32 v85, v100, v85
	v_mul_f32_e32 v86, v100, v86
	v_mul_f32_e32 v87, v100, v87
	v_mul_f32_e32 v76, v100, v76
	v_mul_f32_e32 v77, v100, v77
	v_cvt_pk_bf16_f32 v95, v88, v89
	v_mad_i64_i32 v[88:89], s[10:11], v101, s49, v[120:121]
	v_cvt_pk_bf16_f32 v84, v84, v85
	v_cvt_pk_bf16_f32 v85, v86, v87
	v_cvt_pk_bf16_f32 v86, v76, v77
	v_mul_f32_e32 v76, v100, v78
	v_mul_f32_e32 v77, v100, v79
	v_mul_f32_e32 v78, v159, v150
	v_cmp_gt_f32_e64 s[10:11], s48, v78
	v_lshl_add_u64 v[90:91], v[88:89], 0, v[122:123]
	v_cvt_pk_bf16_f32 v87, v76, v77
	v_cndmask_b32_e64 v78, 0, v154, s[10:11]
	v_fmac_f32_e32 v78, v159, v150
	v_exp_f32_e32 v78, v78
	v_lshl_add_u64 v[76:77], v[88:89], 0, v[112:113]
	global_store_dwordx4 v[90:91], v[92:95], off
	global_store_dwordx4 v[76:77], v[84:87], off
	v_cndmask_b32_e64 v76, 0, v155, s[10:11]
	v_ldexp_f32 v76, v78, v76
	v_mul_f32_e32 v76, 0x3d800000, v76
	v_or_b32_e32 v85, 48, v164
	v_cndmask_b32_e32 v84, 1.0, v76, vcc
	v_mul_f32_e32 v76, v84, v80
	v_mul_f32_e32 v77, v84, v81
	v_mul_f32_e32 v78, v84, v82
	v_mul_f32_e32 v79, v84, v83
	v_mul_f32_e32 v72, v84, v72
	v_mul_f32_e32 v73, v84, v73
	v_cvt_pk_bf16_f32 v76, v76, v77
	v_cvt_pk_bf16_f32 v77, v78, v79
	v_cvt_pk_bf16_f32 v78, v72, v73
	v_mul_f32_e32 v72, v84, v74
	v_mul_f32_e32 v73, v84, v75
	v_mul_f32_e32 v68, v84, v68
	v_mul_f32_e32 v69, v84, v69
	v_mul_f32_e32 v70, v84, v70
	v_mul_f32_e32 v71, v84, v71
	v_mul_f32_e32 v64, v84, v64
	v_mul_f32_e32 v65, v84, v65
	v_cvt_pk_bf16_f32 v79, v72, v73
	v_mad_i64_i32 v[72:73], s[10:11], v85, s49, v[120:121]
	v_cvt_pk_bf16_f32 v68, v68, v69
	v_cvt_pk_bf16_f32 v69, v70, v71
	v_cvt_pk_bf16_f32 v70, v64, v65
	v_mul_f32_e32 v64, v84, v66
	v_mul_f32_e32 v65, v84, v67
	v_lshl_add_u64 v[74:75], v[72:73], 0, v[122:123]
	v_cvt_pk_bf16_f32 v71, v64, v65
	v_lshl_add_u64 v[64:65], v[72:73], 0, v[112:113]
	v_mul_f32_e32 v62, v158, v62
	v_mul_f32_e32 v63, v158, v63
	v_mul_f32_e32 v56, v158, v56
	v_mul_f32_e32 v57, v158, v57
	global_store_dwordx4 v[74:75], v[76:79], off
	global_store_dwordx4 v[64:65], v[68:71], off
	v_add_u32_e32 v64, 0x80, v164
	v_cvt_pk_bf16_f32 v60, v60, v61
	v_cvt_pk_bf16_f32 v61, v62, v63
	v_cvt_pk_bf16_f32 v62, v56, v57
	v_mul_f32_e32 v56, v158, v58
	v_mul_f32_e32 v57, v158, v59
	v_mul_f32_e32 v48, v158, v48
	v_mul_f32_e32 v49, v158, v49
	v_mul_f32_e32 v50, v158, v50
	v_mul_f32_e32 v51, v158, v51
	v_mul_f32_e32 v40, v158, v40
	v_mul_f32_e32 v41, v158, v41
	v_cvt_pk_bf16_f32 v63, v56, v57
	v_mad_i64_i32 v[56:57], s[10:11], v64, s49, v[120:121]
	v_cvt_pk_bf16_f32 v48, v48, v49
	v_cvt_pk_bf16_f32 v49, v50, v51
	v_cvt_pk_bf16_f32 v50, v40, v41
	v_mul_f32_e32 v40, v158, v42
	v_mul_f32_e32 v41, v158, v43
	v_lshl_add_u64 v[58:59], v[56:57], 0, v[122:123]
	v_cvt_pk_bf16_f32 v51, v40, v41
	v_lshl_add_u64 v[40:41], v[56:57], 0, v[112:113]
	global_store_dwordx4 v[58:59], v[60:63], off
	global_store_dwordx4 v[40:41], v[48:51], off
	v_mul_f32_e32 v40, v114, v52
	v_mul_f32_e32 v41, v114, v53
	v_mul_f32_e32 v42, v114, v54
	v_mul_f32_e32 v43, v114, v55
	v_add_u32_e32 v48, 0x90, v164
	v_cvt_pk_bf16_f32 v40, v40, v41
	v_cvt_pk_bf16_f32 v41, v42, v43
	v_mul_f32_e32 v42, v114, v44
	v_mul_f32_e32 v43, v114, v45
	v_mul_f32_e32 v44, v114, v46
	v_mul_f32_e32 v45, v114, v47
	v_mul_f32_e32 v32, v114, v32
	v_mul_f32_e32 v33, v114, v33
	v_mul_f32_e32 v34, v114, v34
	v_mul_f32_e32 v35, v114, v35
	v_mul_f32_e32 v24, v114, v24
	v_mul_f32_e32 v25, v114, v25
	v_cvt_pk_bf16_f32 v42, v42, v43
	v_cvt_pk_bf16_f32 v43, v44, v45
	v_mad_i64_i32 v[44:45], s[10:11], v48, s49, v[120:121]
	v_cvt_pk_bf16_f32 v32, v32, v33
	v_cvt_pk_bf16_f32 v33, v34, v35
	v_cvt_pk_bf16_f32 v34, v24, v25
	v_mul_f32_e32 v24, v114, v26
	v_mul_f32_e32 v25, v114, v27
	v_lshl_add_u64 v[46:47], v[44:45], 0, v[122:123]
	v_cvt_pk_bf16_f32 v35, v24, v25
	v_lshl_add_u64 v[24:25], v[44:45], 0, v[112:113]
	global_store_dwordx4 v[46:47], v[40:43], off
	global_store_dwordx4 v[24:25], v[32:35], off
	v_mul_f32_e32 v24, v100, v36
	v_mul_f32_e32 v25, v100, v37
	v_mul_f32_e32 v26, v100, v38
	v_mul_f32_e32 v27, v100, v39
	v_add_u32_e32 v32, 0xa0, v164
	v_cvt_pk_bf16_f32 v24, v24, v25
	v_cvt_pk_bf16_f32 v25, v26, v27
	v_mul_f32_e32 v26, v100, v28
	v_mul_f32_e32 v27, v100, v29
	v_mul_f32_e32 v28, v100, v30
	v_mul_f32_e32 v29, v100, v31
	v_mul_f32_e32 v16, v100, v16
	v_mul_f32_e32 v17, v100, v17
	v_mul_f32_e32 v18, v100, v18
	v_mul_f32_e32 v19, v100, v19
	v_mul_f32_e32 v8, v100, v8
	v_mul_f32_e32 v9, v100, v9
	v_cvt_pk_bf16_f32 v26, v26, v27
	v_cvt_pk_bf16_f32 v27, v28, v29
	v_mad_i64_i32 v[28:29], s[10:11], v32, s49, v[120:121]
	v_cvt_pk_bf16_f32 v16, v16, v17
	v_cvt_pk_bf16_f32 v17, v18, v19
	v_cvt_pk_bf16_f32 v18, v8, v9
	v_mul_f32_e32 v8, v100, v10
	v_mul_f32_e32 v9, v100, v11
	v_lshl_add_u64 v[30:31], v[28:29], 0, v[122:123]
	v_cvt_pk_bf16_f32 v19, v8, v9
	v_lshl_add_u64 v[8:9], v[28:29], 0, v[112:113]
	global_store_dwordx4 v[30:31], v[24:27], off
	global_store_dwordx4 v[8:9], v[16:19], off
	v_mul_f32_e32 v8, v84, v20
	v_mul_f32_e32 v9, v84, v21
	v_mul_f32_e32 v10, v84, v22
	v_mul_f32_e32 v11, v84, v23
	v_add_u32_e32 v16, 0xb0, v164
	v_cvt_pk_bf16_f32 v8, v8, v9
	v_cvt_pk_bf16_f32 v9, v10, v11
	v_mul_f32_e32 v10, v84, v12
	v_mul_f32_e32 v11, v84, v13
	v_mul_f32_e32 v12, v84, v14
	v_mul_f32_e32 v13, v84, v15
	v_mul_f32_e32 v4, v84, v4
	v_mul_f32_e32 v5, v84, v5
	v_mul_f32_e32 v6, v84, v6
	v_mul_f32_e32 v7, v84, v7
	v_mul_f32_e32 v0, v84, v0
	v_mul_f32_e32 v1, v84, v1
	v_cvt_pk_bf16_f32 v10, v10, v11
	v_cvt_pk_bf16_f32 v11, v12, v13
	v_mad_i64_i32 v[12:13], s[10:11], v16, s49, v[120:121]
	v_cvt_pk_bf16_f32 v4, v4, v5
	v_cvt_pk_bf16_f32 v5, v6, v7
	v_cvt_pk_bf16_f32 v6, v0, v1
	v_mul_f32_e32 v0, v84, v2
	v_mul_f32_e32 v1, v84, v3
	v_lshl_add_u64 v[14:15], v[12:13], 0, v[122:123]
	v_cvt_pk_bf16_f32 v7, v0, v1
	v_lshl_add_u64 v[0:1], v[12:13], 0, v[112:113]
	s_andn2_b64 vcc, exec, s[6:7]
	s_mov_b64 s[6:7], -1
	global_store_dwordx4 v[14:15], v[8:11], off
	global_store_dwordx4 v[0:1], v[4:7], off
	s_cbranch_vccnz .LBB0_326
	s_andn2_b64 vcc, exec, s[12:13]
	s_cbranch_vccnz .LBB0_325
	s_barrier
	s_branch .LBB0_325

.LBB0_388:
	s_bfe_u32 s40, s83, 0x20004
	v_cvt_f32_ubyte0_e32 v142, s40
	v_sub_f32_e32 v142, 0xc0a00000, v142
	v_cmp_gt_f32_e32 vcc, s65, v142
	v_mov_b32_e32 v143, 0x42800000
	s_and_b64 s[38:39], vcc, exec
	v_cndmask_b32_e32 v143, 0, v143, vcc
	v_add_f32_e32 v142, v142, v143
	v_exp_f32_e32 v142, v142
	s_cselect_b32 s38, 0xffffffc0, 0
	s_lshl_b32 s42, s83, 8
	s_and_b32 s42, s42, 0xf00
	v_ldexp_f32 v142, v142, s38
	v_sub_f32_e32 v142, 1.0, v142
	v_add_u32_e32 v150, s42, v138
	v_log_f32_e32 v149, v142
	v_cvt_f32_u32_e32 v142, v150
	s_ashr_i32 s38, s83, 7
	s_ashr_i32 s39, s38, 31
	s_mul_i32 s39, s16, s39
	v_mul_f32_e32 v142, v149, v142
	v_exp_f32_e32 v148, v142
	s_mul_hi_u32 s41, s16, s38
	s_add_i32 s39, s41, s39
	s_mul_i32 s41, s17, s38
	v_mul_f32_e32 v120, v148, v120
	v_mul_f32_e32 v121, v148, v121
	v_mul_f32_e32 v122, v148, v122
	v_mul_f32_e32 v123, v148, v123
	v_mul_f32_e32 v116, v148, v116
	v_mul_f32_e32 v117, v148, v117
	v_cvt_pk_bf16_f32 v120, v120, v121
	v_cvt_pk_bf16_f32 v121, v122, v123
	v_cvt_pk_bf16_f32 v122, v116, v117
	v_mul_f32_e32 v116, v148, v118
	v_mul_f32_e32 v117, v148, v119
	v_cvt_pk_bf16_f32 v123, v116, v117
	v_mul_f32_e32 v116, v148, v124
	v_mul_f32_e32 v117, v148, v125
	v_mul_f32_e32 v118, v148, v126
	v_mul_f32_e32 v119, v148, v127
	v_cvt_pk_bf16_f32 v116, v116, v117
	v_cvt_pk_bf16_f32 v117, v118, v119
	v_or_b32_e32 v118, 16, v150
	v_cvt_f32_u32_e32 v119, v118
	v_mul_f32_e32 v112, v148, v112
	v_mul_f32_e32 v113, v148, v113
	v_cvt_pk_bf16_f32 v118, v112, v113
	v_mul_f32_e32 v112, v148, v114
	v_mul_f32_e32 v113, v148, v115
	v_mul_f32_e32 v114, v149, v119
	v_exp_f32_e32 v114, v114
	s_add_i32 s39, s39, s41
	s_lshl_b32 s41, s83, 6
	s_mul_i32 s38, s16, s38
	v_mul_f32_e32 v108, v114, v108
	v_mul_f32_e32 v109, v114, v109
	v_mul_f32_e32 v110, v114, v110
	v_mul_f32_e32 v111, v114, v111
	v_mul_f32_e32 v100, v114, v100
	v_mul_f32_e32 v101, v114, v101
	v_cvt_pk_bf16_f32 v108, v108, v109
	v_cvt_pk_bf16_f32 v109, v110, v111
	v_cvt_pk_bf16_f32 v110, v100, v101
	v_mul_f32_e32 v100, v114, v102
	v_mul_f32_e32 v101, v114, v103
	v_cvt_pk_bf16_f32 v111, v100, v101
	v_mul_f32_e32 v100, v114, v104
	v_mul_f32_e32 v101, v114, v105
	v_mul_f32_e32 v102, v114, v106
	v_mul_f32_e32 v103, v114, v107
	v_cvt_pk_bf16_f32 v100, v100, v101
	v_cvt_pk_bf16_f32 v101, v102, v103
	v_or_b32_e32 v102, 32, v150
	v_cvt_f32_u32_e32 v103, v102
	v_mul_f32_e32 v96, v114, v96
	v_mul_f32_e32 v97, v114, v97
	v_cvt_pk_bf16_f32 v102, v96, v97
	v_mul_f32_e32 v96, v114, v98
	v_mul_f32_e32 v97, v114, v99
	v_mul_f32_e32 v98, v149, v103
	v_exp_f32_e32 v98, v98
	s_and_b32 s41, s41, 0x1000
	s_or_b32 s41, s41, s42
	s_lshl_b64 s[38:39], s[38:39], 1
	v_mul_f32_e32 v92, v98, v92
	v_mul_f32_e32 v93, v98, v93
	v_mul_f32_e32 v94, v98, v94
	v_mul_f32_e32 v95, v98, v95
	v_mul_f32_e32 v84, v98, v84
	v_mul_f32_e32 v85, v98, v85
	v_cvt_pk_bf16_f32 v92, v92, v93
	v_cvt_pk_bf16_f32 v93, v94, v95
	v_cvt_pk_bf16_f32 v94, v84, v85
	v_mul_f32_e32 v84, v98, v86
	v_mul_f32_e32 v85, v98, v87
	v_cvt_pk_bf16_f32 v95, v84, v85
	v_mul_f32_e32 v84, v98, v88
	v_mul_f32_e32 v85, v98, v89
	v_mul_f32_e32 v86, v98, v90
	v_mul_f32_e32 v87, v98, v91
	v_cvt_pk_bf16_f32 v84, v84, v85
	v_cvt_pk_bf16_f32 v85, v86, v87
	v_or_b32_e32 v86, 48, v150
	v_cvt_f32_u32_e32 v87, v86
	v_mul_f32_e32 v80, v98, v80
	v_mul_f32_e32 v81, v98, v81
	v_cvt_pk_bf16_f32 v86, v80, v81
	v_mul_f32_e32 v80, v98, v82
	v_mul_f32_e32 v81, v98, v83
	v_mul_f32_e32 v82, v149, v87
	v_exp_f32_e32 v82, v82
	s_add_u32 s38, s60, s38
	s_addc_u32 s39, s61, s39
	s_lshl_b32 s41, s41, 12
	s_add_u32 s38, s38, s41
	s_addc_u32 s39, s39, 0
	s_lshl_b32 s40, s40, 10
	v_mul_f32_e32 v64, v82, v64
	v_mul_f32_e32 v65, v82, v65
	v_mul_f32_e32 v66, v82, v66
	v_mul_f32_e32 v67, v82, v67
	v_mul_f32_e32 v56, v82, v56
	v_mul_f32_e32 v57, v82, v57
	s_add_u32 s38, s38, s40
	v_cvt_pk_bf16_f32 v64, v64, v65
	v_cvt_pk_bf16_f32 v65, v66, v67
	v_cvt_pk_bf16_f32 v66, v56, v57
	v_mul_f32_e32 v56, v82, v58
	v_mul_f32_e32 v57, v82, v59
	s_addc_u32 s39, s39, 0
	s_lshl_b32 s40, s45, 9
	v_cvt_pk_bf16_f32 v67, v56, v57
	v_mul_f32_e32 v56, v82, v60
	v_mul_f32_e32 v57, v82, v61
	v_mul_f32_e32 v58, v82, v62
	v_mul_f32_e32 v59, v82, v63
	s_add_u32 s38, s38, s40
	v_cvt_pk_bf16_f32 v56, v56, v57
	v_cvt_pk_bf16_f32 v57, v58, v59
	v_add_u32_e32 v58, 0x80, v150
	s_addc_u32 s39, s39, 0
	v_cvt_f32_u32_e32 v59, v58
	v_lshl_add_u64 v[142:143], s[38:39], 0, v[140:141]
	v_lshl_add_u64 v[142:143], v[142:143], 0, s[6:7]
	v_lshl_add_u64 v[142:143], v[142:143], 0, v[136:137]
	v_mul_f32_e32 v48, v82, v48
	v_mul_f32_e32 v49, v82, v49
	v_cvt_pk_bf16_f32 v119, v112, v113
	v_add_co_u32_e32 v112, vcc, s50, v142
	v_cvt_pk_bf16_f32 v58, v48, v49
	v_mul_f32_e32 v48, v82, v50
	v_mul_f32_e32 v49, v82, v51
	v_mul_f32_e32 v50, v149, v59
	v_addc_co_u32_e32 v113, vcc, 0, v143, vcc
	v_exp_f32_e32 v60, v50
	v_cvt_pk_bf16_f32 v103, v96, v97
	v_add_co_u32_e32 v96, vcc, s66, v142
	global_store_dwordx4 v[142:143], v[120:123], off
	global_store_dwordx4 v[142:143], v[116:119], off offset:256
	v_addc_co_u32_e32 v97, vcc, 0, v143, vcc
	global_store_dwordx4 v[112:113], v[108:111], off
	global_store_dwordx4 v[112:113], v[100:103], off offset:256
	v_cvt_pk_bf16_f32 v87, v80, v81
	v_add_co_u32_e32 v80, vcc, s67, v142
	global_store_dwordx4 v[96:97], v[92:95], off
	global_store_dwordx4 v[96:97], v[84:87], off offset:256
	v_addc_co_u32_e32 v81, vcc, 0, v143, vcc
	v_cvt_pk_bf16_f32 v59, v48, v49
	v_mul_f32_e32 v48, v60, v76
	v_mul_f32_e32 v49, v60, v77
	v_mul_f32_e32 v50, v60, v78
	v_mul_f32_e32 v51, v60, v79
	global_store_dwordx4 v[80:81], v[56:59], off offset:256
	v_cvt_pk_bf16_f32 v48, v48, v49
	v_cvt_pk_bf16_f32 v49, v50, v51
	v_mul_f32_e32 v50, v60, v68
	v_mul_f32_e32 v51, v60, v69
	v_mul_f32_e32 v56, v60, v70
	v_mul_f32_e32 v57, v60, v71
	v_cvt_pk_bf16_f32 v50, v50, v51
	v_cvt_pk_bf16_f32 v51, v56, v57
	v_add_co_u32_e32 v56, vcc, s68, v142
	global_store_dwordx4 v[80:81], v[64:67], off
	s_nop 0
	v_addc_co_u32_e32 v57, vcc, 0, v143, vcc
	global_store_dwordx4 v[56:57], v[48:51], off
	s_nop 1
	v_mul_f32_e32 v48, v60, v72
	v_mul_f32_e32 v49, v60, v73
	v_mul_f32_e32 v50, v60, v74
	v_mul_f32_e32 v51, v60, v75
	v_cvt_pk_bf16_f32 v48, v48, v49
	v_cvt_pk_bf16_f32 v49, v50, v51
	v_add_u32_e32 v50, 0x90, v150
	v_cvt_f32_u32_e32 v58, v50
	v_mul_f32_e32 v50, v60, v52
	v_mul_f32_e32 v51, v60, v53
	v_cvt_pk_bf16_f32 v50, v50, v51
	v_mul_f32_e32 v52, v60, v54
	v_mul_f32_e32 v53, v60, v55
	v_mul_f32_e32 v51, v149, v58
	v_exp_f32_e32 v54, v51
	v_cvt_pk_bf16_f32 v51, v52, v53
	global_store_dwordx4 v[56:57], v[48:51], off offset:256
	v_mul_f32_e32 v44, v54, v44
	v_mul_f32_e32 v45, v54, v45
	v_mul_f32_e32 v46, v54, v46
	v_mul_f32_e32 v47, v54, v47
	v_mul_f32_e32 v36, v54, v36
	v_mul_f32_e32 v37, v54, v37
	v_cvt_pk_bf16_f32 v44, v44, v45
	v_cvt_pk_bf16_f32 v45, v46, v47
	v_cvt_pk_bf16_f32 v46, v36, v37
	v_mul_f32_e32 v36, v54, v38
	v_mul_f32_e32 v37, v54, v39
	v_cvt_pk_bf16_f32 v47, v36, v37
	v_mul_f32_e32 v36, v54, v40
	v_mul_f32_e32 v37, v54, v41
	v_mul_f32_e32 v38, v54, v42
	v_mul_f32_e32 v39, v54, v43
	v_cvt_pk_bf16_f32 v36, v36, v37
	v_cvt_pk_bf16_f32 v37, v38, v39
	v_add_u32_e32 v38, 0xa0, v150
	v_cvt_f32_u32_e32 v39, v38
	v_mul_f32_e32 v32, v54, v32
	v_mul_f32_e32 v33, v54, v33
	v_cvt_pk_bf16_f32 v38, v32, v33
	v_mul_f32_e32 v32, v54, v34
	v_mul_f32_e32 v33, v54, v35
	v_mul_f32_e32 v34, v149, v39
	v_exp_f32_e32 v34, v34
	v_add_co_u32_e32 v48, vcc, s69, v142
	v_cvt_pk_bf16_f32 v39, v32, v33
	v_mul_f32_e32 v28, v34, v28
	v_mul_f32_e32 v29, v34, v29
	v_mul_f32_e32 v30, v34, v30
	v_mul_f32_e32 v31, v34, v31
	v_mul_f32_e32 v20, v34, v20
	v_mul_f32_e32 v21, v34, v21
	v_cvt_pk_bf16_f32 v28, v28, v29
	v_cvt_pk_bf16_f32 v29, v30, v31
	v_cvt_pk_bf16_f32 v30, v20, v21
	v_mul_f32_e32 v20, v34, v22
	v_mul_f32_e32 v21, v34, v23
	v_cvt_pk_bf16_f32 v31, v20, v21
	v_mul_f32_e32 v20, v34, v24
	v_mul_f32_e32 v21, v34, v25
	v_mul_f32_e32 v22, v34, v26
	v_mul_f32_e32 v23, v34, v27
	v_cvt_pk_bf16_f32 v20, v20, v21
	v_cvt_pk_bf16_f32 v21, v22, v23
	v_add_u32_e32 v22, 0xb0, v150
	v_cvt_f32_u32_e32 v23, v22
	v_mul_f32_e32 v16, v34, v16
	v_mul_f32_e32 v17, v34, v17
	v_cvt_pk_bf16_f32 v22, v16, v17
	v_mul_f32_e32 v16, v34, v18
	v_mul_f32_e32 v17, v34, v19
	v_mul_f32_e32 v18, v149, v23
	v_exp_f32_e32 v18, v18
	v_addc_co_u32_e32 v49, vcc, 0, v143, vcc
	v_add_co_u32_e32 v32, vcc, s70, v142
	v_mul_f32_e32 v12, v18, v12
	v_mul_f32_e32 v13, v18, v13
	v_mul_f32_e32 v14, v18, v14
	v_mul_f32_e32 v15, v18, v15
	v_mul_f32_e32 v4, v18, v4
	v_mul_f32_e32 v5, v18, v5
	v_cvt_pk_bf16_f32 v12, v12, v13
	v_cvt_pk_bf16_f32 v13, v14, v15
	v_cvt_pk_bf16_f32 v14, v4, v5
	v_mul_f32_e32 v4, v18, v6
	v_mul_f32_e32 v5, v18, v7
	v_addc_co_u32_e32 v33, vcc, 0, v143, vcc
	v_cvt_pk_bf16_f32 v15, v4, v5
	v_mul_f32_e32 v4, v18, v8
	v_mul_f32_e32 v5, v18, v9
	v_mul_f32_e32 v6, v18, v10
	v_mul_f32_e32 v7, v18, v11
	v_mul_f32_e32 v0, v18, v0
	v_mul_f32_e32 v1, v18, v1
	global_store_dwordx4 v[48:49], v[44:47], off
	global_store_dwordx4 v[48:49], v[36:39], off offset:256
	v_cvt_pk_bf16_f32 v23, v16, v17
	v_add_co_u32_e32 v16, vcc, s71, v142
	v_cvt_pk_bf16_f32 v4, v4, v5
	v_cvt_pk_bf16_f32 v5, v6, v7
	v_cvt_pk_bf16_f32 v6, v0, v1
	v_mul_f32_e32 v0, v18, v2
	v_mul_f32_e32 v1, v18, v3
	global_store_dwordx4 v[32:33], v[28:31], off
	global_store_dwordx4 v[32:33], v[20:23], off offset:256
	v_addc_co_u32_e32 v17, vcc, 0, v143, vcc
	v_cvt_pk_bf16_f32 v7, v0, v1
	global_store_dwordx4 v[16:17], v[12:15], off
	global_store_dwordx4 v[16:17], v[4:7], off offset:256
	s_andn2_b64 vcc, exec, s[24:25]
	s_mov_b64 s[24:25], -1
	s_cbranch_vccnz .LBB0_383
	s_andn2_b64 vcc, exec, s[10:11]
	s_cbranch_vccnz .LBB0_382
	s_barrier
	s_branch .LBB0_382
